# rstd partial loads issued at the top of each tile (idle registers) so the EpiAct/EpiScale epilogue has no memory wait
# baseline (speedup 1.0000x reference)
;     __device__ bool next(int i, Unit& u) const { const long L = (long)i * G + c0; if (L >= n) return false; u.pm = (int)L / nN; u.pn = (int)L % nN; return true; }
;     __host__ __device__ bool next(int i, Unit& u) const {
;         const long L = (long)i * G + c; if (L >= nwg) return false;
;         int wgid = (int)L; { const int q = nwg / NXCD, r = nwg % NXCD, xcd = wgid % NXCD, off = wgid / NXCD; wgid = (xcd < r ? xcd * (q + 1) : r * (q + 1) + (xcd - r) * q) + off; }
;         const int nig = WGM * nN, gid = wgid / nig, fm = gid * WGM, gsz = (nM - fm) < WGM ? (nM - fm) : WGM;
;         u.pm = fm + ((wgid % nig) % gsz); u.pn = (wgid % nig) / gsz; return true;
;     }
; template <class Epi, class Sched, bool ALIGN_EPI = false, bool SP2 = false>
; __device__ __forceinline__ void gemm_phase(PG8_LAS unsigned char* lds, const Gemm g, const Sched& S, const Epi& E) {
;     ...
;     for (;;) {
;         const bool has_next = S.next(ui + 1, nxt);
;         const char* nA = has_next ? (const char*)g.A + (size_t)nxt.pm * tstep : cA; const char* nB = has_next ? (const char*)g.Bt + (size_t)nxt.pn * tstep : cB;
.LBB0_691:
	s_lshl_b32 s99, s6, 8
	s_lshl_b32 s100, s99, 6
	s_add_u32 s100, s80, s100
	s_addc_u32 s101, s81, 0
	v_lshrrev_b32_e32 v249, 6, v252
	v_and_b32_e32 v248, 63, v252
	v_lshlrev_b32_e32 v248, 4, v248
	v_lshl_or_b32 v248, v249, 11, v248
	global_load_dwordx4 v[240:243], v248, s[100:101]
	global_load_dwordx4 v[244:247], v248, s[100:101] offset:1024
	s_add_i32 s50, s50, 1
	s_mul_i32 s4, s50, s55
	s_mul_hi_u32 s5, s50, s84
	s_add_i32 s5, s5, s4
	s_mul_i32 s4, s50, s84
	s_add_u32 s36, s4, s89
	s_addc_u32 s37, s5, s44
	v_cmp_gt_i64_e32 vcc, s[36:37], v[138:139]
	v_cmp_lt_i64_e64 s[4:5], s[36:37], v[136:137]
	s_cbranch_vccnz .LBB0_693
	s_ashr_i32 s7, s36, 31
	s_lshr_b32 s7, s7, 29
	s_add_i32 s7, s36, s7
	s_ashr_i32 s30, s7, 3
	s_and_b32 s7, s7, -8
	s_sub_i32 s7, s36, s7
	s_cmp_lt_i32 s7, 0
	s_cselect_b32 s31, s45, 0x160
	s_mul_i32 s7, s7, s31
	s_add_i32 s7, s7, s30
	s_mul_hi_i32 s30, s7, 0x2e8ba2e9
	s_lshr_b32 s31, s30, 31
	s_ashr_i32 s30, s30, 5
	s_add_i32 s30, s30, s31
	s_lshl_b32 s31, s30, 3
	s_sub_i32 s34, 0x80, s31
	s_min_i32 s34, s34, 8
	s_abs_i32 s35, s34
	v_cvt_f32_u32_e32 v0, s35
	s_sub_i32 s37, 0, s35
	s_mulk_i32 s30, 0xb0
	s_sub_i32 s7, s7, s30
	v_rcp_iflag_f32_e32 v0, v0
	s_abs_i32 s30, s7
	s_xor_b32 s36, s7, s34
	s_ashr_i32 s36, s36, 31
	v_mul_f32_e32 v0, 0x4f7ffffe, v0
	v_cvt_u32_f32_e32 v0, v0
	s_nop 0
	v_readfirstlane_b32 s38, v0
	s_mul_i32 s37, s37, s38
	s_mul_hi_u32 s37, s38, s37
	s_add_i32 s38, s38, s37
	s_mul_hi_u32 s37, s30, s38
	s_mul_i32 s38, s37, s35
	s_sub_i32 s30, s30, s38
	s_add_i32 s39, s37, 1
	s_sub_i32 s38, s30, s35
	s_cmp_ge_u32 s30, s35
	s_cselect_b32 s37, s39, s37
	s_cselect_b32 s30, s38, s30
	s_add_i32 s38, s37, 1
	s_cmp_ge_u32 s30, s35
	s_cselect_b32 s30, s38, s37
	s_xor_b32 s30, s30, s36
	s_sub_i32 s30, s30, s36
	s_mul_i32 s34, s30, s34
	s_sub_i32 s7, s7, s34
	s_add_i32 s34, s31, s7

; #define PG8_GAS __attribute__((address_space(1)))
; __device__ __forceinline__ unsigned pk2_(float lo, float hi) { f32x2c_t v = {lo, hi}; bf16x2c_t b = __builtin_convertvector(v, bf16x2c_t); return __builtin_bit_cast(unsigned, b); }
; __device__ __forceinline__ float row_rstd(const float* parts, int r, int fq) {
;     const f32x4 p = *(const PG8_GAS f32x4*)(parts + (size_t)r * 16 + 4 * fq);
;     float s = (p[0] + p[1]) + (p[2] + p[3]);
;     s += __shfl_xor(s, 16); s += __shfl_xor(s, 32);
;     return rsqrtf(s * (1.0f / 1024.0f) + RMS_EPS);
; }
; __device__ __forceinline__ float silu_f(float x) { return x * __builtin_amdgcn_rcpf(1.0f + __builtin_amdgcn_exp2f(-1.4426950408889634f * x)); }
;     __device__ __forceinline__ void operator()(const f32x4 (&acc)[2][2][4][2], const Unit& u, int wr, int wc, int fr, int fq) const {
;         const int row0 = u.pm * BM + wr * 64 + fr, col0 = u.pn * 128 + wc * 32 + 8 * fq;
;         float rs8[2][4];
; #pragma unroll
;         for (int ai = 0; ai < 2; ++ai)
; #pragma unroll
;             for (int m = 0; m < 4; ++m) rs8[ai][m] = row_rstd(parts, row0 + ai * HALF + m * 16, fq);
; #pragma unroll
;         for (int ai = 0; ai < 2; ++ai)
; #pragma unroll
;             for (int m = 0; m < 4; ++m) {
;                 const int r = row0 + ai * HALF + m * 16; const float s = rs8[ai][m];
;                 float o[8];
; #pragma unroll
;                 for (int n = 0; n < 2; ++n)
; #pragma unroll
;                     for (int i = 0; i < 4; ++i) o[4 * n + i] = silu_f(acc[ai][0][m][n][i] * s) * (acc[ai][1][m][n][i] * s);
;                 u32x4 w; w.x = pk2_(o[0], o[1]); w.y = pk2_(o[2], o[3]); w.z = pk2_(o[4], o[5]); w.w = pk2_(o[6], o[7]);
;                 *(PG8_GAS u32x4*)(O + (size_t)r * 2816 + col0) = w;
.LBB0_697:
	s_lshl_b32 s6, s6, 8
	v_mov_b32_e32 v132, v252
	s_add_i32 s6, s6, s53
	s_mov_b32 s98, s53
	v_bfe_u32 v200, v132, 4, 2
	v_and_or_b32 v160, v132, 15, s6
	v_lshlrev_b32_e32 v132, 4, v200
	v_ashrrev_i32_e32 v161, 31, v160
	v_or_b32_e32 v156, 16, v160
	v_lshl_add_u64 v[190:191], s[80:81], 0, v[132:133]
	v_ashrrev_i32_e32 v157, 31, v156
	v_or_b32_e32 v152, 32, v160
	v_ashrrev_i32_e32 v153, 31, v152
	v_or_b32_e32 v148, 48, v160
	v_ashrrev_i32_e32 v149, 31, v148
	v_add_u32_e32 v146, 0x80, v160
	v_ashrrev_i32_e32 v147, 31, v146
	v_add_u32_e32 v144, 0x90, v160
	v_ashrrev_i32_e32 v145, 31, v144
	v_and_b32_e32 v140, 64, v165
	v_add_u32_e32 v147, 64, v140
	v_add_u32_e32 v142, 0xa0, v160
	v_add_u32_e32 v140, 0xb0, v160
	v_xor_b32_e32 v132, 16, v165
	v_cmp_lt_i32_e32 vcc, v132, v147
	v_xor_b32_e32 v145, 32, v165
	s_nop 0
	v_cndmask_b32_e32 v132, v165, v132, vcc
	v_lshlrev_b32_e32 v132, 2, v132
	v_cmp_lt_i32_e32 vcc, v145, v147
	v_mov_b64_e32 v[174:175], s[28:29]
	v_add_f32_e32 v240, v240, v241
	v_add_f32_e32 v242, v242, v243
	v_add_f32_e32 v244, v244, v245
	v_add_f32_e32 v246, v246, v247
	v_add_f32_e32 v240, v240, v242
	v_add_f32_e32 v244, v244, v246
	v_mov_b32_e32 v242, 0x358637bd
	s_nop 0
	v_add_f32_dpp v241, v240, v240 quad_perm:[1,0,3,2] row_mask:0xf bank_mask:0xf
	v_add_f32_dpp v245, v244, v244 quad_perm:[1,0,3,2] row_mask:0xf bank_mask:0xf
	v_and_b32_e32 v243, 60, v252
	v_lshl_add_u32 v243, v249, 7, v243
	v_add_f32_dpp v240, v241, v241 quad_perm:[2,3,0,1] row_mask:0xf bank_mask:0xf
	v_add_f32_dpp v244, v245, v245 quad_perm:[2,3,0,1] row_mask:0xf bank_mask:0xf
	v_add_u32_e32 v243, 0x21000, v243
	v_and_b32_e32 v246, 15, v252
	v_fmamk_f32 v240, v240, 0x3a800000, v242
	v_fmamk_f32 v244, v244, 0x3a800000, v242
	v_add_u32_e32 v246, s98, v246
	v_rsq_f32_e32 v240, v240
	v_rsq_f32_e32 v244, v244
	v_lshlrev_b32_e32 v246, 2, v246
	v_add_u32_e32 v246, 0x21000, v246
	ds_write_b32 v243, v240
	ds_write_b32 v243, v244 offset:64
	s_waitcnt lgkmcnt(0)
	s_barrier
	ds_read_b32 v166, v246
	ds_read_b32 v172, v246 offset:64
	ds_read_b32 v164, v246 offset:128
	ds_read_b32 v162, v246 offset:192
	ds_read_b32 v158, v246 offset:512
	ds_read_b32 v154, v246 offset:576
	ds_read_b32 v150, v246 offset:640
	ds_read_b32 v132, v246 offset:704
	s_waitcnt lgkmcnt(0)
	s_lshl_b32 s6, s60, 7
	v_lshl_or_b32 v141, v200, 3, s6
	v_pk_mul_f32 v[124:125], v[124:125], v[166:167] op_sel_hi:[1,0]
	v_or_b32_e32 v168, s54, v141
	v_mul_f32_e32 v141, 0xbfb8aa3b, v124
	v_exp_f32_e32 v141, v141
	v_mul_f32_e32 v143, 0xbfb8aa3b, v125
	v_exp_f32_e32 v143, v143
	v_pk_mul_f32 v[126:127], v[126:127], v[166:167] op_sel_hi:[1,0]
	v_add_f32_e32 v141, 1.0, v141
	v_rcp_f32_e32 v170, v141
	v_add_f32_e32 v141, 1.0, v143
	v_mul_f32_e32 v143, 0xbfb8aa3b, v126
	v_exp_f32_e32 v143, v143
	v_mul_f32_e32 v145, 0xbfb8aa3b, v127
	v_exp_f32_e32 v145, v145
	v_rcp_f32_e32 v171, v141
	v_add_f32_e32 v141, 1.0, v143
	v_rcp_f32_e32 v174, v141
	v_add_f32_e32 v141, 1.0, v145
	v_rcp_f32_e32 v175, v141
	v_pk_mul_f32 v[124:125], v[124:125], v[170:171]
	v_pk_mul_f32 v[116:117], v[116:117], v[166:167] op_sel_hi:[1,0]
	v_pk_mul_f32 v[120:121], v[120:121], v[166:167] op_sel_hi:[1,0]
	v_pk_mul_f32 v[116:117], v[116:117], v[124:125]
	v_pk_mul_f32 v[124:125], v[126:127], v[174:175]
	v_mul_f32_e32 v126, 0xbfb8aa3b, v120
	v_mul_f32_e32 v127, 0xbfb8aa3b, v121
	v_exp_f32_e32 v126, v126
	v_exp_f32_e32 v127, v127
	v_pk_mul_f32 v[118:119], v[118:119], v[166:167] op_sel_hi:[1,0]
	v_pk_mul_f32 v[122:123], v[122:123], v[166:167] op_sel_hi:[1,0]
	v_pk_mul_f32 v[118:119], v[118:119], v[124:125]
	v_add_f32_e32 v124, 1.0, v126
	v_add_f32_e32 v125, 1.0, v127
	v_mul_f32_e32 v126, 0xbfb8aa3b, v122
	v_mul_f32_e32 v127, 0xbfb8aa3b, v123
	v_exp_f32_e32 v126, v126
	v_exp_f32_e32 v127, v127
	v_rcp_f32_e32 v124, v124
	v_rcp_f32_e32 v125, v125
	v_add_f32_e32 v126, 1.0, v126
	v_add_f32_e32 v127, 1.0, v127
	v_rcp_f32_e32 v126, v126
	v_rcp_f32_e32 v127, v127
	v_pk_mul_f32 v[120:121], v[120:121], v[124:125]
	v_pk_mul_f32 v[112:113], v[112:113], v[166:167] op_sel_hi:[1,0]
	v_pk_mul_f32 v[114:115], v[114:115], v[166:167] op_sel_hi:[1,0]
	v_pk_mul_f32 v[112:113], v[112:113], v[120:121]
	v_pk_mul_f32 v[120:121], v[122:123], v[126:127]
	v_ashrrev_i32_e32 v169, 31, v168
	v_pk_mul_f32 v[114:115], v[114:115], v[120:121]
	v_cvt_pk_bf16_f32 v116, v116, v117
	v_cvt_pk_bf16_f32 v117, v118, v119
	v_cvt_pk_bf16_f32 v118, v112, v113
	v_mov_b64_e32 v[112:113], s[14:15]
	v_cvt_pk_bf16_f32 v119, v114, v115
	v_mad_i64_i32 v[120:121], s[6:7], v160, s59, v[112:113]
	v_lshlrev_b64 v[114:115], 1, v[168:169]
	v_pk_mul_f32 v[108:109], v[108:109], v[172:173] op_sel_hi:[1,0]
	v_lshl_add_u64 v[120:121], v[120:121], 0, v[114:115]
	v_mul_f32_e32 v122, 0xbfb8aa3b, v108
	v_mul_f32_e32 v123, 0xbfb8aa3b, v109
	v_pk_mul_f32 v[110:111], v[110:111], v[172:173] op_sel_hi:[1,0]
	v_exp_f32_e32 v122, v122
	v_exp_f32_e32 v123, v123
	global_store_dwordx4 v[120:121], v[116:119], off
	v_pk_mul_f32 v[100:101], v[100:101], v[172:173] op_sel_hi:[1,0]
	v_pk_mul_f32 v[104:105], v[104:105], v[172:173] op_sel_hi:[1,0]
	v_mul_f32_e32 v118, 0xbfb8aa3b, v110
	v_mul_f32_e32 v119, 0xbfb8aa3b, v111
	v_exp_f32_e32 v118, v118
	v_exp_f32_e32 v119, v119
	v_add_f32_e32 v116, 1.0, v122
	v_add_f32_e32 v117, 1.0, v123
	v_rcp_f32_e32 v116, v116
	v_rcp_f32_e32 v117, v117
	v_add_f32_e32 v118, 1.0, v118
	v_add_f32_e32 v119, 1.0, v119
	v_rcp_f32_e32 v118, v118
	v_rcp_f32_e32 v119, v119
	v_pk_mul_f32 v[108:109], v[108:109], v[116:117]
	v_pk_mul_f32 v[102:103], v[102:103], v[172:173] op_sel_hi:[1,0]
	v_pk_mul_f32 v[100:101], v[100:101], v[108:109]
	v_pk_mul_f32 v[108:109], v[110:111], v[118:119]
	v_mul_f32_e32 v110, 0xbfb8aa3b, v104
; #define PG8_GAS __attribute__((address_space(1)))
; __device__ __forceinline__ unsigned pk2_(float lo, float hi) { f32x2c_t v = {lo, hi}; bf16x2c_t b = __builtin_convertvector(v, bf16x2c_t); return __builtin_bit_cast(unsigned, b); }
; __device__ __forceinline__ float silu_f(float x) { return x * __builtin_amdgcn_rcpf(1.0f + __builtin_amdgcn_exp2f(-1.4426950408889634f * x)); }
;     __device__ __forceinline__ void operator()(const f32x4 (&acc)[2][2][4][2], const Unit& u, int wr, int wc, int fr, int fq) const {
;     ...
;             for (int m = 0; m < 4; ++m) {
;                 const int r = row0 + ai * HALF + m * 16; const float s = rs8[ai][m];
;                 float o[8];
; #pragma unroll
;                 for (int n = 0; n < 2; ++n)
; #pragma unroll
;                     for (int i = 0; i < 4; ++i) o[4 * n + i] = silu_f(acc[ai][0][m][n][i] * s) * (acc[ai][1][m][n][i] * s);
;                 u32x4 w; w.x = pk2_(o[0], o[1]); w.y = pk2_(o[2], o[3]); w.z = pk2_(o[4], o[5]); w.w = pk2_(o[6], o[7]);
;                 *(PG8_GAS u32x4*)(O + (size_t)r * 2816 + col0) = w;
	v_mul_f32_e32 v111, 0xbfb8aa3b, v105
	v_exp_f32_e32 v110, v110
	v_exp_f32_e32 v111, v111
	v_pk_mul_f32 v[106:107], v[106:107], v[172:173] op_sel_hi:[1,0]
	v_pk_mul_f32 v[102:103], v[102:103], v[108:109]
	v_add_f32_e32 v108, 1.0, v110
	v_add_f32_e32 v109, 1.0, v111
	v_mul_f32_e32 v110, 0xbfb8aa3b, v106
	v_mul_f32_e32 v111, 0xbfb8aa3b, v107
	v_exp_f32_e32 v110, v110
	v_exp_f32_e32 v111, v111
	v_rcp_f32_e32 v108, v108
	v_rcp_f32_e32 v109, v109
	v_add_f32_e32 v110, 1.0, v110
	v_add_f32_e32 v111, 1.0, v111
	v_rcp_f32_e32 v110, v110
	v_rcp_f32_e32 v111, v111
	v_pk_mul_f32 v[104:105], v[104:105], v[108:109]
	v_pk_mul_f32 v[96:97], v[96:97], v[172:173] op_sel_hi:[1,0]
	v_pk_mul_f32 v[98:99], v[98:99], v[172:173] op_sel_hi:[1,0]
	v_pk_mul_f32 v[104:105], v[96:97], v[104:105]
	v_pk_mul_f32 v[96:97], v[106:107], v[110:111]
	v_pk_mul_f32 v[92:93], v[92:93], v[164:165] op_sel_hi:[1,0]
	v_pk_mul_f32 v[106:107], v[98:99], v[96:97]
	v_cvt_pk_bf16_f32 v96, v100, v101
	v_mad_i64_i32 v[100:101], s[6:7], v156, s59, v[112:113]
	v_cvt_pk_bf16_f32 v97, v102, v103
	v_cvt_pk_bf16_f32 v98, v104, v105
	v_cvt_pk_bf16_f32 v99, v106, v107
	v_lshl_add_u64 v[100:101], v[100:101], 0, v[114:115]
	v_mul_f32_e32 v102, 0xbfb8aa3b, v92
	v_mul_f32_e32 v103, 0xbfb8aa3b, v93
	v_pk_mul_f32 v[94:95], v[94:95], v[164:165] op_sel_hi:[1,0]
	v_exp_f32_e32 v102, v102
	v_exp_f32_e32 v103, v103
	global_store_dwordx4 v[100:101], v[96:99], off
	v_pk_mul_f32 v[84:85], v[84:85], v[164:165] op_sel_hi:[1,0]
	v_pk_mul_f32 v[88:89], v[88:89], v[164:165] op_sel_hi:[1,0]
	v_mul_f32_e32 v98, 0xbfb8aa3b, v94
	v_mul_f32_e32 v99, 0xbfb8aa3b, v95
	v_exp_f32_e32 v98, v98
	v_exp_f32_e32 v99, v99
	v_add_f32_e32 v96, 1.0, v102
	v_add_f32_e32 v97, 1.0, v103
	v_rcp_f32_e32 v96, v96
	v_rcp_f32_e32 v97, v97
	v_add_f32_e32 v98, 1.0, v98
	v_add_f32_e32 v99, 1.0, v99
	v_rcp_f32_e32 v98, v98
	v_rcp_f32_e32 v99, v99
	v_pk_mul_f32 v[92:93], v[92:93], v[96:97]
	v_pk_mul_f32 v[86:87], v[86:87], v[164:165] op_sel_hi:[1,0]
	v_pk_mul_f32 v[84:85], v[84:85], v[92:93]
	v_pk_mul_f32 v[92:93], v[94:95], v[98:99]
	v_mul_f32_e32 v94, 0xbfb8aa3b, v88
	v_mul_f32_e32 v95, 0xbfb8aa3b, v89
	v_exp_f32_e32 v94, v94
	v_exp_f32_e32 v95, v95
	v_pk_mul_f32 v[90:91], v[90:91], v[164:165] op_sel_hi:[1,0]
	v_pk_mul_f32 v[86:87], v[86:87], v[92:93]
	v_add_f32_e32 v92, 1.0, v94
	v_add_f32_e32 v93, 1.0, v95
	v_mul_f32_e32 v94, 0xbfb8aa3b, v90
	v_mul_f32_e32 v95, 0xbfb8aa3b, v91
	v_exp_f32_e32 v94, v94
	v_exp_f32_e32 v95, v95
	v_rcp_f32_e32 v92, v92
	v_rcp_f32_e32 v93, v93
	v_add_f32_e32 v94, 1.0, v94
	v_add_f32_e32 v95, 1.0, v95
	v_rcp_f32_e32 v94, v94
	v_rcp_f32_e32 v95, v95
	v_pk_mul_f32 v[88:89], v[88:89], v[92:93]
	v_pk_mul_f32 v[80:81], v[80:81], v[164:165] op_sel_hi:[1,0]
	v_pk_mul_f32 v[82:83], v[82:83], v[164:165] op_sel_hi:[1,0]
	v_pk_mul_f32 v[88:89], v[80:81], v[88:89]
	v_pk_mul_f32 v[80:81], v[90:91], v[94:95]
	v_pk_mul_f32 v[76:77], v[76:77], v[162:163] op_sel_hi:[1,0]
	v_pk_mul_f32 v[90:91], v[82:83], v[80:81]
	v_cvt_pk_bf16_f32 v80, v84, v85
	v_mad_i64_i32 v[84:85], s[6:7], v152, s59, v[112:113]
	v_cvt_pk_bf16_f32 v81, v86, v87
	v_cvt_pk_bf16_f32 v82, v88, v89
	v_cvt_pk_bf16_f32 v83, v90, v91
	v_lshl_add_u64 v[84:85], v[84:85], 0, v[114:115]
	v_mul_f32_e32 v86, 0xbfb8aa3b, v76
	v_mul_f32_e32 v87, 0xbfb8aa3b, v77
	v_pk_mul_f32 v[78:79], v[78:79], v[162:163] op_sel_hi:[1,0]
	v_exp_f32_e32 v86, v86
	v_exp_f32_e32 v87, v87
	global_store_dwordx4 v[84:85], v[80:83], off
	v_pk_mul_f32 v[68:69], v[68:69], v[162:163] op_sel_hi:[1,0]
	v_pk_mul_f32 v[72:73], v[72:73], v[162:163] op_sel_hi:[1,0]
	v_mul_f32_e32 v82, 0xbfb8aa3b, v78
	v_mul_f32_e32 v83, 0xbfb8aa3b, v79
	v_exp_f32_e32 v82, v82
	v_exp_f32_e32 v83, v83
	v_add_f32_e32 v80, 1.0, v86
	v_add_f32_e32 v81, 1.0, v87
	v_rcp_f32_e32 v80, v80
	v_rcp_f32_e32 v81, v81
	v_add_f32_e32 v82, 1.0, v82
	v_add_f32_e32 v83, 1.0, v83
	v_rcp_f32_e32 v82, v82
	v_rcp_f32_e32 v83, v83
	v_pk_mul_f32 v[76:77], v[76:77], v[80:81]
	v_pk_mul_f32 v[70:71], v[70:71], v[162:163] op_sel_hi:[1,0]
	v_pk_mul_f32 v[68:69], v[68:69], v[76:77]
	v_pk_mul_f32 v[76:77], v[78:79], v[82:83]
	v_mul_f32_e32 v78, 0xbfb8aa3b, v72
	v_mul_f32_e32 v79, 0xbfb8aa3b, v73
	v_exp_f32_e32 v78, v78
	v_exp_f32_e32 v79, v79
	v_pk_mul_f32 v[74:75], v[74:75], v[162:163] op_sel_hi:[1,0]
	v_pk_mul_f32 v[70:71], v[70:71], v[76:77]
	v_add_f32_e32 v76, 1.0, v78
	v_add_f32_e32 v77, 1.0, v79
	v_mul_f32_e32 v78, 0xbfb8aa3b, v74
	v_mul_f32_e32 v79, 0xbfb8aa3b, v75
	v_exp_f32_e32 v78, v78
	v_exp_f32_e32 v79, v79
	v_rcp_f32_e32 v76, v76
	v_rcp_f32_e32 v77, v77
	v_add_f32_e32 v78, 1.0, v78
	v_add_f32_e32 v79, 1.0, v79
	v_rcp_f32_e32 v78, v78
	v_rcp_f32_e32 v79, v79
	v_pk_mul_f32 v[72:73], v[72:73], v[76:77]
	v_pk_mul_f32 v[64:65], v[64:65], v[162:163] op_sel_hi:[1,0]
	v_pk_mul_f32 v[66:67], v[66:67], v[162:163] op_sel_hi:[1,0]
	v_pk_mul_f32 v[72:73], v[64:65], v[72:73]
	v_pk_mul_f32 v[64:65], v[74:75], v[78:79]
	v_pk_mul_f32 v[60:61], v[60:61], v[158:159] op_sel_hi:[1,0]
	v_pk_mul_f32 v[74:75], v[66:67], v[64:65]
	v_cvt_pk_bf16_f32 v64, v68, v69
	v_mad_i64_i32 v[68:69], s[6:7], v148, s59, v[112:113]
	v_cvt_pk_bf16_f32 v65, v70, v71
	v_cvt_pk_bf16_f32 v66, v72, v73
	v_cvt_pk_bf16_f32 v67, v74, v75
	v_lshl_add_u64 v[68:69], v[68:69], 0, v[114:115]
	v_mul_f32_e32 v70, 0xbfb8aa3b, v60
	v_mul_f32_e32 v71, 0xbfb8aa3b, v61
	v_pk_mul_f32 v[62:63], v[62:63], v[158:159] op_sel_hi:[1,0]
	v_exp_f32_e32 v70, v70
	v_exp_f32_e32 v71, v71
	global_store_dwordx4 v[68:69], v[64:67], off
	v_pk_mul_f32 v[52:53], v[52:53], v[158:159] op_sel_hi:[1,0]
	v_pk_mul_f32 v[56:57], v[56:57], v[158:159] op_sel_hi:[1,0]
	v_mul_f32_e32 v66, 0xbfb8aa3b, v62
	v_mul_f32_e32 v67, 0xbfb8aa3b, v63
; #define PG8_GAS __attribute__((address_space(1)))
; __device__ __forceinline__ unsigned pk2_(float lo, float hi) { f32x2c_t v = {lo, hi}; bf16x2c_t b = __builtin_convertvector(v, bf16x2c_t); return __builtin_bit_cast(unsigned, b); }
; __device__ __forceinline__ float silu_f(float x) { return x * __builtin_amdgcn_rcpf(1.0f + __builtin_amdgcn_exp2f(-1.4426950408889634f * x)); }
;     __device__ __forceinline__ void operator()(const f32x4 (&acc)[2][2][4][2], const Unit& u, int wr, int wc, int fr, int fq) const {
;     ...
;             for (int m = 0; m < 4; ++m) {
;                 const int r = row0 + ai * HALF + m * 16; const float s = rs8[ai][m];
;                 float o[8];
; #pragma unroll
;                 for (int n = 0; n < 2; ++n)
; #pragma unroll
;                     for (int i = 0; i < 4; ++i) o[4 * n + i] = silu_f(acc[ai][0][m][n][i] * s) * (acc[ai][1][m][n][i] * s);
;                 u32x4 w; w.x = pk2_(o[0], o[1]); w.y = pk2_(o[2], o[3]); w.z = pk2_(o[4], o[5]); w.w = pk2_(o[6], o[7]);
;                 *(PG8_GAS u32x4*)(O + (size_t)r * 2816 + col0) = w;
	v_exp_f32_e32 v66, v66
	v_exp_f32_e32 v67, v67
	v_add_f32_e32 v64, 1.0, v70
	v_add_f32_e32 v65, 1.0, v71
	v_rcp_f32_e32 v64, v64
	v_rcp_f32_e32 v65, v65
	v_add_f32_e32 v66, 1.0, v66
	v_add_f32_e32 v67, 1.0, v67
	v_rcp_f32_e32 v66, v66
	v_rcp_f32_e32 v67, v67
	v_pk_mul_f32 v[60:61], v[60:61], v[64:65]
	v_pk_mul_f32 v[54:55], v[54:55], v[158:159] op_sel_hi:[1,0]
	v_pk_mul_f32 v[52:53], v[52:53], v[60:61]
	v_pk_mul_f32 v[60:61], v[62:63], v[66:67]
	v_mul_f32_e32 v62, 0xbfb8aa3b, v56
	v_mul_f32_e32 v63, 0xbfb8aa3b, v57
	v_exp_f32_e32 v62, v62
	v_exp_f32_e32 v63, v63
	v_pk_mul_f32 v[58:59], v[58:59], v[158:159] op_sel_hi:[1,0]
	v_pk_mul_f32 v[54:55], v[54:55], v[60:61]
	v_add_f32_e32 v60, 1.0, v62
	v_add_f32_e32 v61, 1.0, v63
	v_mul_f32_e32 v62, 0xbfb8aa3b, v58
	v_mul_f32_e32 v63, 0xbfb8aa3b, v59
	v_exp_f32_e32 v62, v62
	v_exp_f32_e32 v63, v63
	v_rcp_f32_e32 v60, v60
	v_rcp_f32_e32 v61, v61
	v_add_f32_e32 v62, 1.0, v62
	v_add_f32_e32 v63, 1.0, v63
	v_rcp_f32_e32 v62, v62
	v_rcp_f32_e32 v63, v63
	v_pk_mul_f32 v[56:57], v[56:57], v[60:61]
	v_pk_mul_f32 v[48:49], v[48:49], v[158:159] op_sel_hi:[1,0]
	v_pk_mul_f32 v[50:51], v[50:51], v[158:159] op_sel_hi:[1,0]
	v_pk_mul_f32 v[56:57], v[48:49], v[56:57]
	v_pk_mul_f32 v[48:49], v[58:59], v[62:63]
	v_pk_mul_f32 v[44:45], v[44:45], v[154:155] op_sel_hi:[1,0]
	v_pk_mul_f32 v[58:59], v[50:51], v[48:49]
	v_cvt_pk_bf16_f32 v48, v52, v53
	v_mad_i64_i32 v[52:53], s[6:7], v146, s59, v[112:113]
	v_cvt_pk_bf16_f32 v49, v54, v55
	v_cvt_pk_bf16_f32 v50, v56, v57
	v_cvt_pk_bf16_f32 v51, v58, v59
	v_lshl_add_u64 v[52:53], v[52:53], 0, v[114:115]
	v_mul_f32_e32 v54, 0xbfb8aa3b, v44
	v_mul_f32_e32 v55, 0xbfb8aa3b, v45
	v_pk_mul_f32 v[46:47], v[46:47], v[154:155] op_sel_hi:[1,0]
	v_exp_f32_e32 v54, v54
	v_exp_f32_e32 v55, v55
	global_store_dwordx4 v[52:53], v[48:51], off
	v_pk_mul_f32 v[36:37], v[36:37], v[154:155] op_sel_hi:[1,0]
	v_pk_mul_f32 v[40:41], v[40:41], v[154:155] op_sel_hi:[1,0]
	v_mul_f32_e32 v50, 0xbfb8aa3b, v46
	v_mul_f32_e32 v51, 0xbfb8aa3b, v47
	v_exp_f32_e32 v50, v50
	v_exp_f32_e32 v51, v51
	v_add_f32_e32 v48, 1.0, v54
	v_add_f32_e32 v49, 1.0, v55
	v_rcp_f32_e32 v48, v48
	v_rcp_f32_e32 v49, v49
	v_add_f32_e32 v50, 1.0, v50
	v_add_f32_e32 v51, 1.0, v51
	v_rcp_f32_e32 v50, v50
	v_rcp_f32_e32 v51, v51
	v_pk_mul_f32 v[44:45], v[44:45], v[48:49]
	v_pk_mul_f32 v[38:39], v[38:39], v[154:155] op_sel_hi:[1,0]
	v_pk_mul_f32 v[36:37], v[36:37], v[44:45]
	v_pk_mul_f32 v[44:45], v[46:47], v[50:51]
	v_mul_f32_e32 v46, 0xbfb8aa3b, v40
	v_mul_f32_e32 v47, 0xbfb8aa3b, v41
	v_exp_f32_e32 v46, v46
	v_exp_f32_e32 v47, v47
	v_pk_mul_f32 v[42:43], v[42:43], v[154:155] op_sel_hi:[1,0]
	v_pk_mul_f32 v[38:39], v[38:39], v[44:45]
	v_add_f32_e32 v44, 1.0, v46
	v_add_f32_e32 v45, 1.0, v47
	v_mul_f32_e32 v46, 0xbfb8aa3b, v42
	v_mul_f32_e32 v47, 0xbfb8aa3b, v43
	v_exp_f32_e32 v46, v46
	v_exp_f32_e32 v47, v47
	v_rcp_f32_e32 v44, v44
	v_rcp_f32_e32 v45, v45
	v_add_f32_e32 v46, 1.0, v46
	v_add_f32_e32 v47, 1.0, v47
	v_rcp_f32_e32 v46, v46
	v_rcp_f32_e32 v47, v47
	v_pk_mul_f32 v[40:41], v[40:41], v[44:45]
	v_pk_mul_f32 v[32:33], v[32:33], v[154:155] op_sel_hi:[1,0]
	v_pk_mul_f32 v[34:35], v[34:35], v[154:155] op_sel_hi:[1,0]
	v_pk_mul_f32 v[40:41], v[32:33], v[40:41]
	v_pk_mul_f32 v[32:33], v[42:43], v[46:47]
	v_pk_mul_f32 v[28:29], v[28:29], v[150:151] op_sel_hi:[1,0]
	v_pk_mul_f32 v[42:43], v[34:35], v[32:33]
	v_cvt_pk_bf16_f32 v32, v36, v37
	v_mad_i64_i32 v[36:37], s[6:7], v144, s59, v[112:113]
	v_cvt_pk_bf16_f32 v33, v38, v39
	v_cvt_pk_bf16_f32 v34, v40, v41
	v_cvt_pk_bf16_f32 v35, v42, v43
	v_lshl_add_u64 v[36:37], v[36:37], 0, v[114:115]
	v_mul_f32_e32 v38, 0xbfb8aa3b, v28
	v_mul_f32_e32 v39, 0xbfb8aa3b, v29
	v_pk_mul_f32 v[30:31], v[30:31], v[150:151] op_sel_hi:[1,0]
	v_exp_f32_e32 v38, v38
	v_exp_f32_e32 v39, v39
	global_store_dwordx4 v[36:37], v[32:35], off
; #define PG8_GAS __attribute__((address_space(1)))
; __device__ __forceinline__ unsigned pk2_(float lo, float hi) { f32x2c_t v = {lo, hi}; bf16x2c_t b = __builtin_convertvector(v, bf16x2c_t); return __builtin_bit_cast(unsigned, b); }
; __device__ __forceinline__ float silu_f(float x) { return x * __builtin_amdgcn_rcpf(1.0f + __builtin_amdgcn_exp2f(-1.4426950408889634f * x)); }
;     __device__ __forceinline__ void operator()(const f32x4 (&acc)[2][2][4][2], const Unit& u, int wr, int wc, int fr, int fq) const {
;     ...
;             for (int m = 0; m < 4; ++m) {
;                 const int r = row0 + ai * HALF + m * 16; const float s = rs8[ai][m];
;                 float o[8];
; #pragma unroll
;                 for (int n = 0; n < 2; ++n)
; #pragma unroll
;                     for (int i = 0; i < 4; ++i) o[4 * n + i] = silu_f(acc[ai][0][m][n][i] * s) * (acc[ai][1][m][n][i] * s);
;                 u32x4 w; w.x = pk2_(o[0], o[1]); w.y = pk2_(o[2], o[3]); w.z = pk2_(o[4], o[5]); w.w = pk2_(o[6], o[7]);
;                 *(PG8_GAS u32x4*)(O + (size_t)r * 2816 + col0) = w;
;             }
	v_pk_mul_f32 v[20:21], v[20:21], v[150:151] op_sel_hi:[1,0]
	v_pk_mul_f32 v[24:25], v[24:25], v[150:151] op_sel_hi:[1,0]
	v_mul_f32_e32 v34, 0xbfb8aa3b, v30
	v_mul_f32_e32 v35, 0xbfb8aa3b, v31
	v_exp_f32_e32 v34, v34
	v_exp_f32_e32 v35, v35
	v_add_f32_e32 v32, 1.0, v38
	v_add_f32_e32 v33, 1.0, v39
	v_rcp_f32_e32 v32, v32
	v_rcp_f32_e32 v33, v33
	v_add_f32_e32 v34, 1.0, v34
	v_add_f32_e32 v35, 1.0, v35
	v_rcp_f32_e32 v34, v34
	v_rcp_f32_e32 v35, v35
	v_pk_mul_f32 v[28:29], v[28:29], v[32:33]
	v_pk_mul_f32 v[22:23], v[22:23], v[150:151] op_sel_hi:[1,0]
	v_pk_mul_f32 v[20:21], v[20:21], v[28:29]
	v_pk_mul_f32 v[28:29], v[30:31], v[34:35]
	v_mul_f32_e32 v30, 0xbfb8aa3b, v24
	v_mul_f32_e32 v31, 0xbfb8aa3b, v25
	v_exp_f32_e32 v30, v30
	v_exp_f32_e32 v31, v31
	v_pk_mul_f32 v[26:27], v[26:27], v[150:151] op_sel_hi:[1,0]
	v_pk_mul_f32 v[22:23], v[22:23], v[28:29]
	v_add_f32_e32 v28, 1.0, v30
	v_add_f32_e32 v29, 1.0, v31
	v_mul_f32_e32 v30, 0xbfb8aa3b, v26
	v_mul_f32_e32 v31, 0xbfb8aa3b, v27
	v_exp_f32_e32 v30, v30
	v_exp_f32_e32 v31, v31
	v_rcp_f32_e32 v28, v28
	v_rcp_f32_e32 v29, v29
	v_add_f32_e32 v30, 1.0, v30
	v_add_f32_e32 v31, 1.0, v31
	v_rcp_f32_e32 v30, v30
	v_rcp_f32_e32 v31, v31
	v_pk_mul_f32 v[24:25], v[24:25], v[28:29]
	v_pk_mul_f32 v[16:17], v[16:17], v[150:151] op_sel_hi:[1,0]
	v_pk_mul_f32 v[18:19], v[18:19], v[150:151] op_sel_hi:[1,0]
	v_pk_mul_f32 v[24:25], v[16:17], v[24:25]
	v_pk_mul_f32 v[16:17], v[26:27], v[30:31]
	v_pk_mul_f32 v[12:13], v[12:13], v[132:133] op_sel_hi:[1,0]
	v_pk_mul_f32 v[26:27], v[18:19], v[16:17]
	v_cvt_pk_bf16_f32 v16, v20, v21
	v_mad_i64_i32 v[20:21], s[6:7], v142, s59, v[112:113]
	v_cvt_pk_bf16_f32 v17, v22, v23
	v_cvt_pk_bf16_f32 v18, v24, v25
	v_cvt_pk_bf16_f32 v19, v26, v27
	v_lshl_add_u64 v[20:21], v[20:21], 0, v[114:115]
	v_mul_f32_e32 v22, 0xbfb8aa3b, v12
	v_mul_f32_e32 v23, 0xbfb8aa3b, v13
	v_pk_mul_f32 v[14:15], v[14:15], v[132:133] op_sel_hi:[1,0]
	v_exp_f32_e32 v22, v22
	v_exp_f32_e32 v23, v23
	global_store_dwordx4 v[20:21], v[16:19], off
	v_pk_mul_f32 v[4:5], v[4:5], v[132:133] op_sel_hi:[1,0]
	v_pk_mul_f32 v[8:9], v[8:9], v[132:133] op_sel_hi:[1,0]
	v_mul_f32_e32 v18, 0xbfb8aa3b, v14
	v_mul_f32_e32 v19, 0xbfb8aa3b, v15
	v_exp_f32_e32 v18, v18
	v_exp_f32_e32 v19, v19
	v_add_f32_e32 v16, 1.0, v22
	v_add_f32_e32 v17, 1.0, v23
	v_rcp_f32_e32 v16, v16
	v_rcp_f32_e32 v17, v17
	v_add_f32_e32 v18, 1.0, v18
	v_add_f32_e32 v19, 1.0, v19
	v_rcp_f32_e32 v18, v18
	v_rcp_f32_e32 v19, v19
	v_pk_mul_f32 v[12:13], v[12:13], v[16:17]
	v_pk_mul_f32 v[6:7], v[6:7], v[132:133] op_sel_hi:[1,0]
	v_pk_mul_f32 v[4:5], v[4:5], v[12:13]
	v_pk_mul_f32 v[12:13], v[14:15], v[18:19]
	v_mul_f32_e32 v14, 0xbfb8aa3b, v8
	v_mul_f32_e32 v15, 0xbfb8aa3b, v9
	v_exp_f32_e32 v14, v14
	v_exp_f32_e32 v15, v15
	v_pk_mul_f32 v[10:11], v[10:11], v[132:133] op_sel_hi:[1,0]
	v_pk_mul_f32 v[6:7], v[6:7], v[12:13]
	v_add_f32_e32 v12, 1.0, v14
	v_add_f32_e32 v13, 1.0, v15
	v_mul_f32_e32 v14, 0xbfb8aa3b, v10
	v_mul_f32_e32 v15, 0xbfb8aa3b, v11
	v_exp_f32_e32 v14, v14
	v_exp_f32_e32 v15, v15
	v_rcp_f32_e32 v12, v12
	v_rcp_f32_e32 v13, v13
	v_add_f32_e32 v14, 1.0, v14
	v_add_f32_e32 v15, 1.0, v15
	v_rcp_f32_e32 v14, v14
	v_rcp_f32_e32 v15, v15
	v_pk_mul_f32 v[8:9], v[8:9], v[12:13]
	v_pk_mul_f32 v[0:1], v[0:1], v[132:133] op_sel_hi:[1,0]
	v_pk_mul_f32 v[2:3], v[2:3], v[132:133] op_sel_hi:[1,0]
	v_pk_mul_f32 v[8:9], v[0:1], v[8:9]
	v_pk_mul_f32 v[0:1], v[10:11], v[14:15]
	s_andn2_b64 vcc, exec, s[4:5]
	v_pk_mul_f32 v[10:11], v[2:3], v[0:1]
	v_cvt_pk_bf16_f32 v0, v4, v5
	v_mad_i64_i32 v[4:5], s[6:7], v140, s59, v[112:113]
	v_cvt_pk_bf16_f32 v1, v6, v7
	v_cvt_pk_bf16_f32 v2, v8, v9
	v_cvt_pk_bf16_f32 v3, v10, v11
	v_lshl_add_u64 v[4:5], v[4:5], 0, v[114:115]
	s_mov_b64 s[4:5], -1
	global_store_dwordx4 v[4:5], v[0:3], off
	s_cbranch_vccnz .LBB0_690
	s_andn2_b64 vcc, exec, s[12:13]
	s_cbranch_vccnz .LBB0_689
	s_barrier
	s_branch .LBB0_689

; #define PG8_GAS __attribute__((address_space(1)))
;     __device__ bool next(int i, Unit& u) const { const long L = (long)i * G + c0; if (L >= n) return false; u.pm = (int)L / nN; u.pn = (int)L % nN; return true; }
;     __host__ __device__ bool next(int i, Unit& u) const {
;         const long L = (long)i * G + c; if (L >= nwg) return false;
;         int wgid = (int)L; { const int q = nwg / NXCD, r = nwg % NXCD, xcd = wgid % NXCD, off = wgid / NXCD; wgid = (xcd < r ? xcd * (q + 1) : r * (q + 1) + (xcd - r) * q) + off; }
;         const int nig = WGM * nN, gid = wgid / nig, fm = gid * WGM, gsz = (nM - fm) < WGM ? (nM - fm) : WGM;
;         u.pm = fm + ((wgid % nig) % gsz); u.pn = (wgid % nig) / gsz; return true;
; __device__ __forceinline__ float row_rstd(const float* parts, int r, int fq) {
;     const f32x4 p = *(const PG8_GAS f32x4*)(parts + (size_t)r * 16 + 4 * fq);
.LBB0_841:
	s_lshl_b32 s99, s8, 8
	s_lshl_b32 s100, s99, 6
	s_add_u32 s100, s16, s100
	s_addc_u32 s101, s17, 0
	v_lshrrev_b32_e32 v249, 6, v252
	v_and_b32_e32 v248, 63, v252
	v_lshlrev_b32_e32 v248, 4, v248
	v_lshl_or_b32 v248, v249, 11, v248
	global_load_dwordx4 v[240:243], v248, s[100:101]
	global_load_dwordx4 v[244:247], v248, s[100:101] offset:1024
	s_add_i32 s52, s52, 1
	s_mul_i32 s6, s52, s57
	s_mul_hi_u32 s7, s52, s84
	s_add_i32 s7, s7, s6
	s_mul_i32 s6, s52, s84
	s_add_u32 s38, s6, s89
	s_addc_u32 s39, s7, s46
	v_cmp_gt_i64_e32 vcc, s[38:39], v[138:139]
	v_cmp_lt_i64_e64 s[6:7], s[38:39], v[136:137]
	s_cbranch_vccnz .LBB0_843
	s_ashr_i32 s9, s38, 31
	s_lshr_b32 s9, s9, 29
	s_add_i32 s9, s38, s9
	s_ashr_i32 s34, s9, 3
	s_and_b32 s9, s9, -8
	s_sub_i32 s9, s38, s9
	s_cmp_lt_i32 s9, 0
	s_cselect_b32 s35, s47, 0xf0
	s_mul_i32 s9, s9, s35
	s_add_i32 s9, s9, s34
	s_mul_hi_i32 s34, s9, 0x88888889
	s_add_i32 s34, s34, s9
	s_lshr_b32 s35, s34, 31
	s_ashr_i32 s34, s34, 6
	s_add_i32 s34, s34, s35
	s_lshl_b32 s35, s34, 3
	s_sub_i32 s36, 0x80, s35
	s_min_i32 s36, s36, 8
	s_abs_i32 s37, s36
	v_cvt_f32_u32_e32 v0, s37
	s_sub_i32 s39, 0, s37
	s_mulk_i32 s34, 0x78
	s_sub_i32 s9, s9, s34
	v_rcp_iflag_f32_e32 v0, v0
	s_abs_i32 s34, s9
	s_xor_b32 s38, s9, s36
	s_ashr_i32 s38, s38, 31
	v_mul_f32_e32 v0, 0x4f7ffffe, v0
	v_cvt_u32_f32_e32 v0, v0
	s_nop 0
	v_readfirstlane_b32 s40, v0
	s_mul_i32 s39, s39, s40
	s_mul_hi_u32 s39, s40, s39
	s_add_i32 s40, s40, s39
	s_mul_hi_u32 s39, s34, s40
	s_mul_i32 s40, s39, s37
	s_sub_i32 s34, s34, s40
	s_add_i32 s41, s39, 1
	s_sub_i32 s40, s34, s37
	s_cmp_ge_u32 s34, s37
	s_cselect_b32 s39, s41, s39
	s_cselect_b32 s34, s40, s34
	s_add_i32 s40, s39, 1
	s_cmp_ge_u32 s34, s37
	s_cselect_b32 s34, s40, s39
	s_xor_b32 s34, s34, s38
	s_sub_i32 s34, s34, s38
	s_mul_i32 s36, s34, s36
	s_sub_i32 s9, s9, s36
	s_add_i32 s36, s35, s9

; #define PG8_GAS __attribute__((address_space(1)))
; __device__ __forceinline__ unsigned pk2_(float lo, float hi) { f32x2c_t v = {lo, hi}; bf16x2c_t b = __builtin_convertvector(v, bf16x2c_t); return __builtin_bit_cast(unsigned, b); }
; __device__ __forceinline__ float row_rstd(const float* parts, int r, int fq) {
;     const f32x4 p = *(const PG8_GAS f32x4*)(parts + (size_t)r * 16 + 4 * fq);
;     float s = (p[0] + p[1]) + (p[2] + p[3]);
;     s += __shfl_xor(s, 16); s += __shfl_xor(s, 32);
;     return rsqrtf(s * (1.0f / 1024.0f) + RMS_EPS);
; }
;     __device__ __forceinline__ void operator()(const f32x4 (&acc)[2][2][4][2], const Unit& u, int wr, int wc, int fr, int fq) const {
;         const int row0 = u.pm * BM + wr * 64 + fr, col0 = u.pn * BM + wc * 32 + 8 * fq;
;         float rs8[2][4];
; #pragma unroll
;         for (int ai = 0; ai < 2; ++ai)
; #pragma unroll
;             for (int m = 0; m < 4; ++m) { const int r = row0 + ai * HALF + m * 16; rs8[ai][m] = MODE == 0 ? row_rstd(sc, r, fq) : (MODE == 1 ? ((const PG8_GAS float*)sc)[r] : 1.f); }
;         f32x4 cs[2][2];
;         if (MODE == 2) {
; #pragma unroll
;             for (int bj = 0; bj < 2; ++bj)
; #pragma unroll
;                 for (int n = 0; n < 2; ++n) cs[bj][n] = *(const PG8_GAS f32x4*)(sc + col0 + bj * HALF + 4 * n);
;         }
; #pragma unroll
;         for (int ai = 0; ai < 2; ++ai)
; #pragma unroll
;             for (int m = 0; m < 4; ++m) {
;                 const int r = row0 + ai * HALF + m * 16;
;                 const float s = rs8[ai][m];
; #pragma unroll
;                 for (int bj = 0; bj < 2; ++bj) {
;                     f32x4 v0 = acc[ai][bj][m][0], v1 = acc[ai][bj][m][1];
;                     if (MODE == 2) { v0 = v0 * cs[bj][0]; v1 = v1 * cs[bj][1]; } else { v0 = v0 * s; v1 = v1 * s; }
;                     u32x4 w; w.x = pk2_(v0[0], v0[1]); w.y = pk2_(v0[2], v0[3]); w.z = pk2_(v1[0], v1[1]); w.w = pk2_(v1[2], v1[3]);
;                     *(PG8_GAS u32x4*)(O + (size_t)r * ldc + col0 + bj * HALF) = w;
;                 }
.LBB0_847:
	s_lshl_b32 s8, s8, 8
	v_mov_b32_e32 v132, v252
	s_add_i32 s8, s8, s55
	s_mov_b32 s98, s55
	v_bfe_u32 v196, v132, 4, 2
	v_and_or_b32 v152, v132, 15, s8
	v_lshlrev_b32_e32 v132, 4, v196
	v_ashrrev_i32_e32 v153, 31, v152
	v_or_b32_e32 v150, 16, v152
	v_lshl_add_u64 v[186:187], s[16:17], 0, v[132:133]
	v_ashrrev_i32_e32 v151, 31, v150
	v_or_b32_e32 v154, 32, v152
	v_ashrrev_i32_e32 v155, 31, v154
	v_or_b32_e32 v146, 48, v152
	v_ashrrev_i32_e32 v147, 31, v146
	v_add_u32_e32 v148, 0x80, v152
	v_ashrrev_i32_e32 v149, 31, v148
	v_add_u32_e32 v142, 0x90, v152
	v_and_b32_e32 v140, 64, v161
	v_add_u32_e32 v147, 64, v140
	v_add_u32_e32 v144, 0xa0, v152
	v_add_u32_e32 v140, 0xb0, v152
	v_ashrrev_i32_e32 v145, 31, v144
	v_xor_b32_e32 v132, 16, v161
	v_cmp_lt_i32_e32 vcc, v132, v147
	v_xor_b32_e32 v143, 32, v161
	s_nop 0
	v_cndmask_b32_e32 v132, v161, v132, vcc
	v_lshlrev_b32_e32 v132, 2, v132
	v_cmp_lt_i32_e32 vcc, v143, v147
	v_mov_b64_e32 v[170:171], s[30:31]
	v_add_f32_e32 v240, v240, v241
	v_add_f32_e32 v242, v242, v243
	v_add_f32_e32 v244, v244, v245
	v_add_f32_e32 v246, v246, v247
	v_add_f32_e32 v240, v240, v242
	v_add_f32_e32 v244, v244, v246
	v_mov_b32_e32 v242, 0x358637bd
	s_nop 0
	v_add_f32_dpp v241, v240, v240 quad_perm:[1,0,3,2] row_mask:0xf bank_mask:0xf
	v_add_f32_dpp v245, v244, v244 quad_perm:[1,0,3,2] row_mask:0xf bank_mask:0xf
	v_and_b32_e32 v243, 60, v252
	v_lshl_add_u32 v243, v249, 7, v243
	v_add_f32_dpp v240, v241, v241 quad_perm:[2,3,0,1] row_mask:0xf bank_mask:0xf
	v_add_f32_dpp v244, v245, v245 quad_perm:[2,3,0,1] row_mask:0xf bank_mask:0xf
	v_add_u32_e32 v243, 0x21000, v243
	v_and_b32_e32 v246, 15, v252
	v_fmamk_f32 v240, v240, 0x3a800000, v242
	v_fmamk_f32 v244, v244, 0x3a800000, v242
	v_add_u32_e32 v246, s98, v246
	v_rsq_f32_e32 v240, v240
	v_rsq_f32_e32 v244, v244
	v_lshlrev_b32_e32 v246, 2, v246
	v_add_u32_e32 v246, 0x21000, v246
	ds_write_b32 v243, v240
	ds_write_b32 v243, v244 offset:64
	s_waitcnt lgkmcnt(0)
	s_barrier
	ds_read_b32 v162, v246
	ds_read_b32 v168, v246 offset:64
	ds_read_b32 v172, v246 offset:128
	ds_read_b32 v174, v246 offset:192
	ds_read_b32 v176, v246 offset:512
	ds_read_b32 v164, v246 offset:576
	ds_read_b32 v156, v246 offset:640
	ds_read_b32 v132, v246 offset:704
	s_waitcnt lgkmcnt(0)
	s_lshl_b32 s8, s62, 8
	v_lshl_or_b32 v141, v196, 3, s8
	v_or_b32_e32 v166, s56, v141
	v_pk_mul_f32 v[126:127], v[126:127], v[162:163] op_sel_hi:[1,0]
	v_pk_mul_f32 v[124:125], v[124:125], v[162:163] op_sel_hi:[1,0]
	v_pk_mul_f32 v[120:121], v[120:121], v[162:163] op_sel_hi:[1,0]
	v_ashrrev_i32_e32 v167, 31, v166
	v_pk_mul_f32 v[122:123], v[122:123], v[162:163] op_sel_hi:[1,0]
	v_cvt_pk_bf16_f32 v124, v124, v125
	v_cvt_pk_bf16_f32 v125, v126, v127
	v_cvt_pk_bf16_f32 v126, v120, v121
	v_mov_b64_e32 v[120:121], s[14:15]
	v_cvt_pk_bf16_f32 v127, v122, v123
	v_mad_i64_i32 v[152:153], s[8:9], v152, s61, v[120:121]
	v_lshlrev_b64 v[122:123], 1, v[166:167]
	v_lshl_add_u64 v[152:153], v[152:153], 0, v[122:123]
	global_store_dwordx4 v[152:153], v[124:127], off
	v_pk_mul_f32 v[114:115], v[114:115], v[162:163] op_sel_hi:[1,0]
	v_pk_mul_f32 v[112:113], v[112:113], v[162:163] op_sel_hi:[1,0]
	v_pk_mul_f32 v[124:125], v[106:107], v[162:163] op_sel_hi:[1,0]
	v_pk_mul_f32 v[106:107], v[104:105], v[162:163] op_sel_hi:[1,0]
	v_cvt_pk_bf16_f32 v104, v112, v113
	v_cvt_pk_bf16_f32 v105, v114, v115
	v_cvt_pk_bf16_f32 v106, v106, v107
	v_cvt_pk_bf16_f32 v107, v124, v125
	global_store_dwordx4 v[152:153], v[104:107], off offset:256
	v_pk_mul_f32 v[108:109], v[108:109], v[168:169] op_sel_hi:[1,0]
	v_pk_mul_f32 v[110:111], v[110:111], v[168:169] op_sel_hi:[1,0]
	v_pk_mul_f32 v[106:107], v[118:119], v[168:169] op_sel_hi:[1,0]
	v_pk_mul_f32 v[104:105], v[116:117], v[168:169] op_sel_hi:[1,0]
	v_pk_mul_f32 v[98:99], v[98:99], v[168:169] op_sel_hi:[1,0]
	v_cvt_pk_bf16_f32 v104, v104, v105
	v_cvt_pk_bf16_f32 v105, v106, v107
	v_cvt_pk_bf16_f32 v106, v108, v109
	v_mad_i64_i32 v[108:109], s[8:9], v150, s61, v[120:121]
	v_cvt_pk_bf16_f32 v107, v110, v111
	v_lshl_add_u64 v[108:109], v[108:109], 0, v[122:123]
	global_store_dwordx4 v[108:109], v[104:107], off
	v_pk_mul_f32 v[96:97], v[96:97], v[168:169] op_sel_hi:[1,0]
	v_pk_mul_f32 v[92:93], v[92:93], v[172:173] op_sel_hi:[1,0]
	v_pk_mul_f32 v[104:105], v[90:91], v[168:169] op_sel_hi:[1,0]
	v_pk_mul_f32 v[90:91], v[88:89], v[168:169] op_sel_hi:[1,0]
	v_cvt_pk_bf16_f32 v88, v96, v97
	v_cvt_pk_bf16_f32 v89, v98, v99
	v_cvt_pk_bf16_f32 v90, v90, v91
	v_cvt_pk_bf16_f32 v91, v104, v105
	global_store_dwordx4 v[108:109], v[88:91], off offset:256
	v_pk_mul_f32 v[94:95], v[94:95], v[172:173] op_sel_hi:[1,0]
	v_pk_mul_f32 v[82:83], v[82:83], v[172:173] op_sel_hi:[1,0]
	v_pk_mul_f32 v[90:91], v[102:103], v[172:173] op_sel_hi:[1,0]
	v_pk_mul_f32 v[88:89], v[100:101], v[172:173] op_sel_hi:[1,0]
	v_pk_mul_f32 v[80:81], v[80:81], v[172:173] op_sel_hi:[1,0]
	v_cvt_pk_bf16_f32 v88, v88, v89
	v_cvt_pk_bf16_f32 v89, v90, v91
	v_cvt_pk_bf16_f32 v90, v92, v93
	v_mad_i64_i32 v[92:93], s[8:9], v154, s61, v[120:121]
	v_cvt_pk_bf16_f32 v91, v94, v95
	v_lshl_add_u64 v[92:93], v[92:93], 0, v[122:123]
	global_store_dwordx4 v[92:93], v[88:91], off
	v_pk_mul_f32 v[76:77], v[76:77], v[174:175] op_sel_hi:[1,0]
; #define PG8_GAS __attribute__((address_space(1)))
; __device__ __forceinline__ unsigned pk2_(float lo, float hi) { f32x2c_t v = {lo, hi}; bf16x2c_t b = __builtin_convertvector(v, bf16x2c_t); return __builtin_bit_cast(unsigned, b); }
;     __device__ __forceinline__ void operator()(const f32x4 (&acc)[2][2][4][2], const Unit& u, int wr, int wc, int fr, int fq) const {
;     ...
; #pragma unroll
;         for (int ai = 0; ai < 2; ++ai)
; #pragma unroll
;             for (int m = 0; m < 4; ++m) {
;                 const int r = row0 + ai * HALF + m * 16;
;                 const float s = rs8[ai][m];
; #pragma unroll
;                 for (int bj = 0; bj < 2; ++bj) {
;                     f32x4 v0 = acc[ai][bj][m][0], v1 = acc[ai][bj][m][1];
;                     if (MODE == 2) { v0 = v0 * cs[bj][0]; v1 = v1 * cs[bj][1]; } else { v0 = v0 * s; v1 = v1 * s; }
;                     u32x4 w; w.x = pk2_(v0[0], v0[1]); w.y = pk2_(v0[2], v0[3]); w.z = pk2_(v1[0], v1[1]); w.w = pk2_(v1[2], v1[3]);
;                     *(PG8_GAS u32x4*)(O + (size_t)r * ldc + col0 + bj * HALF) = w;
;                 }
;             }
	v_pk_mul_f32 v[78:79], v[78:79], v[174:175] op_sel_hi:[1,0]
	v_pk_mul_f32 v[88:89], v[74:75], v[172:173] op_sel_hi:[1,0]
	v_pk_mul_f32 v[74:75], v[72:73], v[172:173] op_sel_hi:[1,0]
	v_cvt_pk_bf16_f32 v72, v80, v81
	v_cvt_pk_bf16_f32 v73, v82, v83
	v_cvt_pk_bf16_f32 v74, v74, v75
	v_cvt_pk_bf16_f32 v75, v88, v89
	global_store_dwordx4 v[92:93], v[72:75], off offset:256
	v_pk_mul_f32 v[70:71], v[70:71], v[174:175] op_sel_hi:[1,0]
	v_pk_mul_f32 v[68:69], v[68:69], v[174:175] op_sel_hi:[1,0]
	v_pk_mul_f32 v[74:75], v[86:87], v[174:175] op_sel_hi:[1,0]
	v_pk_mul_f32 v[72:73], v[84:85], v[174:175] op_sel_hi:[1,0]
	v_pk_mul_f32 v[60:61], v[60:61], v[176:177] op_sel_hi:[1,0]
	v_cvt_pk_bf16_f32 v72, v72, v73
	v_cvt_pk_bf16_f32 v73, v74, v75
	v_cvt_pk_bf16_f32 v74, v76, v77
	v_mad_i64_i32 v[76:77], s[8:9], v146, s61, v[120:121]
	v_cvt_pk_bf16_f32 v75, v78, v79
	v_lshl_add_u64 v[76:77], v[76:77], 0, v[122:123]
	global_store_dwordx4 v[76:77], v[72:75], off
	v_pk_mul_f32 v[62:63], v[62:63], v[176:177] op_sel_hi:[1,0]
	v_pk_mul_f32 v[50:51], v[50:51], v[176:177] op_sel_hi:[1,0]
	v_pk_mul_f32 v[72:73], v[66:67], v[174:175] op_sel_hi:[1,0]
	v_pk_mul_f32 v[66:67], v[64:65], v[174:175] op_sel_hi:[1,0]
	v_cvt_pk_bf16_f32 v64, v68, v69
	v_cvt_pk_bf16_f32 v65, v70, v71
	v_cvt_pk_bf16_f32 v66, v66, v67
	v_cvt_pk_bf16_f32 v67, v72, v73
	global_store_dwordx4 v[76:77], v[64:67], off offset:256
	v_pk_mul_f32 v[48:49], v[48:49], v[176:177] op_sel_hi:[1,0]
	v_pk_mul_f32 v[44:45], v[44:45], v[164:165] op_sel_hi:[1,0]
	v_pk_mul_f32 v[64:65], v[58:59], v[176:177] op_sel_hi:[1,0]
	v_pk_mul_f32 v[58:59], v[56:57], v[176:177] op_sel_hi:[1,0]
	v_cvt_pk_bf16_f32 v56, v60, v61
	v_mad_i64_i32 v[60:61], s[8:9], v148, s61, v[120:121]
	v_cvt_pk_bf16_f32 v57, v62, v63
	v_cvt_pk_bf16_f32 v58, v58, v59
	v_cvt_pk_bf16_f32 v59, v64, v65
	v_lshl_add_u64 v[60:61], v[60:61], 0, v[122:123]
	global_store_dwordx4 v[60:61], v[56:59], off
	v_pk_mul_f32 v[46:47], v[46:47], v[164:165] op_sel_hi:[1,0]
	v_pk_mul_f32 v[34:35], v[34:35], v[164:165] op_sel_hi:[1,0]
	v_pk_mul_f32 v[56:57], v[42:43], v[176:177] op_sel_hi:[1,0]
	v_pk_mul_f32 v[42:43], v[40:41], v[176:177] op_sel_hi:[1,0]
	v_cvt_pk_bf16_f32 v40, v48, v49
	v_cvt_pk_bf16_f32 v41, v50, v51
	v_cvt_pk_bf16_f32 v42, v42, v43
	v_cvt_pk_bf16_f32 v43, v56, v57
	global_store_dwordx4 v[60:61], v[40:43], off offset:256
	v_pk_mul_f32 v[32:33], v[32:33], v[164:165] op_sel_hi:[1,0]
	v_pk_mul_f32 v[28:29], v[28:29], v[156:157] op_sel_hi:[1,0]
	v_pk_mul_f32 v[42:43], v[54:55], v[164:165] op_sel_hi:[1,0]
	v_pk_mul_f32 v[40:41], v[52:53], v[164:165] op_sel_hi:[1,0]
	v_pk_mul_f32 v[30:31], v[30:31], v[156:157] op_sel_hi:[1,0]
	v_cvt_pk_bf16_f32 v40, v40, v41
	v_cvt_pk_bf16_f32 v41, v42, v43
	v_cvt_pk_bf16_f32 v42, v44, v45
	v_mad_i64_i32 v[44:45], s[8:9], v142, s61, v[120:121]
	v_cvt_pk_bf16_f32 v43, v46, v47
	v_lshl_add_u64 v[44:45], v[44:45], 0, v[122:123]
	global_store_dwordx4 v[44:45], v[40:43], off
	v_pk_mul_f32 v[18:19], v[18:19], v[156:157] op_sel_hi:[1,0]
	v_pk_mul_f32 v[16:17], v[16:17], v[156:157] op_sel_hi:[1,0]
	v_pk_mul_f32 v[40:41], v[26:27], v[164:165] op_sel_hi:[1,0]
	v_pk_mul_f32 v[26:27], v[24:25], v[164:165] op_sel_hi:[1,0]
	v_cvt_pk_bf16_f32 v24, v32, v33
	v_cvt_pk_bf16_f32 v25, v34, v35
	v_cvt_pk_bf16_f32 v26, v26, v27
	v_cvt_pk_bf16_f32 v27, v40, v41
	global_store_dwordx4 v[44:45], v[24:27], off offset:256
	v_pk_mul_f32 v[12:13], v[12:13], v[132:133] op_sel_hi:[1,0]
	v_pk_mul_f32 v[14:15], v[14:15], v[132:133] op_sel_hi:[1,0]
	v_pk_mul_f32 v[26:27], v[38:39], v[156:157] op_sel_hi:[1,0]
	v_pk_mul_f32 v[24:25], v[36:37], v[156:157] op_sel_hi:[1,0]
	v_pk_mul_f32 v[6:7], v[6:7], v[132:133] op_sel_hi:[1,0]
	v_cvt_pk_bf16_f32 v24, v24, v25
	v_cvt_pk_bf16_f32 v25, v26, v27
	v_cvt_pk_bf16_f32 v26, v28, v29
	v_mad_i64_i32 v[28:29], s[8:9], v144, s61, v[120:121]
	v_cvt_pk_bf16_f32 v27, v30, v31
	v_lshl_add_u64 v[28:29], v[28:29], 0, v[122:123]
	global_store_dwordx4 v[28:29], v[24:27], off
	v_pk_mul_f32 v[4:5], v[4:5], v[132:133] op_sel_hi:[1,0]
	s_andn2_b64 vcc, exec, s[6:7]
	v_pk_mul_f32 v[24:25], v[10:11], v[156:157] op_sel_hi:[1,0]
	v_pk_mul_f32 v[10:11], v[8:9], v[156:157] op_sel_hi:[1,0]
	v_cvt_pk_bf16_f32 v8, v16, v17
	v_cvt_pk_bf16_f32 v9, v18, v19
	v_cvt_pk_bf16_f32 v10, v10, v11
	v_cvt_pk_bf16_f32 v11, v24, v25
	global_store_dwordx4 v[28:29], v[8:11], off offset:256
	s_mov_b64 s[6:7], -1
	s_nop 0
	v_pk_mul_f32 v[10:11], v[22:23], v[132:133] op_sel_hi:[1,0]
	v_pk_mul_f32 v[8:9], v[20:21], v[132:133] op_sel_hi:[1,0]
	s_nop 0
	v_cvt_pk_bf16_f32 v8, v8, v9
	v_cvt_pk_bf16_f32 v9, v10, v11
	v_cvt_pk_bf16_f32 v10, v12, v13
	v_mad_i64_i32 v[12:13], s[8:9], v140, s61, v[120:121]
	v_cvt_pk_bf16_f32 v11, v14, v15
	v_lshl_add_u64 v[12:13], v[12:13], 0, v[122:123]
	global_store_dwordx4 v[12:13], v[8:11], off
	s_nop 1
	v_pk_mul_f32 v[8:9], v[2:3], v[132:133] op_sel_hi:[1,0]
	v_pk_mul_f32 v[2:3], v[0:1], v[132:133] op_sel_hi:[1,0]
	v_cvt_pk_bf16_f32 v0, v4, v5
	v_cvt_pk_bf16_f32 v1, v6, v7
	v_cvt_pk_bf16_f32 v2, v2, v3
	v_cvt_pk_bf16_f32 v3, v8, v9
	global_store_dwordx4 v[12:13], v[0:3], off offset:256
	s_cbranch_vccnz .LBB0_840
	s_andn2_b64 vcc, exec, s[12:13]
	s_cbranch_vccnz .LBB0_839
	s_barrier
	s_branch .LBB0_839

; #define PG8_GAS __attribute__((address_space(1)))
;     __device__ bool next(int i, Unit& u) const { const long L = (long)i * G + c0; if (L >= n) return false; u.pm = (int)L / nN; u.pn = (int)L % nN; return true; }
;     __host__ __device__ bool next(int i, Unit& u) const {
;         const long L = (long)i * G + c; if (L >= nwg) return false;
;         int wgid = (int)L; { const int q = nwg / NXCD, r = nwg % NXCD, xcd = wgid % NXCD, off = wgid / NXCD; wgid = (xcd < r ? xcd * (q + 1) : r * (q + 1) + (xcd - r) * q) + off; }
;         const int nig = WGM * nN, gid = wgid / nig, fm = gid * WGM, gsz = (nM - fm) < WGM ? (nM - fm) : WGM;
;         u.pm = fm + ((wgid % nig) % gsz); u.pn = (wgid % nig) / gsz; return true;
; __device__ __forceinline__ float row_rstd(const float* parts, int r, int fq) {
;     const f32x4 p = *(const PG8_GAS f32x4*)(parts + (size_t)r * 16 + 4 * fq);
.LBB0_1452:
	s_lshl_b32 s99, s8, 8
	s_lshl_b32 s100, s99, 6
	s_add_u32 s100, s16, s100
	s_addc_u32 s101, s17, 0
	v_lshrrev_b32_e32 v249, 6, v252
	v_and_b32_e32 v248, 63, v252
	v_lshlrev_b32_e32 v248, 4, v248
	v_lshl_or_b32 v248, v249, 11, v248
	global_load_dwordx4 v[240:243], v248, s[100:101]
	global_load_dwordx4 v[244:247], v248, s[100:101] offset:1024
	s_add_i32 s52, s52, 1
	s_mul_i32 s6, s52, s57
	s_mul_hi_u32 s7, s52, s76
	s_add_i32 s7, s7, s6
	s_mul_i32 s6, s52, s76
	s_add_u32 s38, s6, s77
	s_addc_u32 s39, s7, s29
	v_cmp_gt_i64_e32 vcc, s[38:39], v[138:139]
	v_cmp_lt_i64_e64 s[6:7], s[38:39], v[136:137]
	s_cbranch_vccnz .LBB0_1458
	s_ashr_i32 s9, s38, 31
	s_lshr_b32 s9, s9, 29
	s_add_i32 s9, s38, s9
	s_and_b32 s33, s9, -8
	s_sub_i32 s33, s38, s33
	s_cmp_gt_i32 s33, -1
	s_mov_b64 s[34:35], -1
	s_cbranch_scc0 .LBB0_1455
	s_lshl_b32 s36, s33, 6
	s_mov_b64 s[34:35], 0

; #define PG8_GAS __attribute__((address_space(1)))
; __device__ __forceinline__ unsigned pk2_(float lo, float hi) { f32x2c_t v = {lo, hi}; bf16x2c_t b = __builtin_convertvector(v, bf16x2c_t); return __builtin_bit_cast(unsigned, b); }
; __device__ __forceinline__ float row_rstd(const float* parts, int r, int fq) {
;     const f32x4 p = *(const PG8_GAS f32x4*)(parts + (size_t)r * 16 + 4 * fq);
;     float s = (p[0] + p[1]) + (p[2] + p[3]);
;     s += __shfl_xor(s, 16); s += __shfl_xor(s, 32);
;     return rsqrtf(s * (1.0f / 1024.0f) + RMS_EPS);
; }
;     __device__ __forceinline__ void operator()(const f32x4 (&acc)[2][2][4][2], const Unit& u, int wr, int wc, int fr, int fq) const {
;         const int row0 = u.pm * BM + wr * 64 + fr, col0 = u.pn * BM + wc * 32 + 8 * fq;
;         float rs8[2][4];
; #pragma unroll
;         for (int ai = 0; ai < 2; ++ai)
; #pragma unroll
;             for (int m = 0; m < 4; ++m) { const int r = row0 + ai * HALF + m * 16; rs8[ai][m] = MODE == 0 ? row_rstd(sc, r, fq) : (MODE == 1 ? ((const PG8_GAS float*)sc)[r] : 1.f); }
;         f32x4 cs[2][2];
;         if (MODE == 2) {
; #pragma unroll
;             for (int bj = 0; bj < 2; ++bj)
; #pragma unroll
;                 for (int n = 0; n < 2; ++n) cs[bj][n] = *(const PG8_GAS f32x4*)(sc + col0 + bj * HALF + 4 * n);
;         }
; #pragma unroll
;         for (int ai = 0; ai < 2; ++ai)
; #pragma unroll
;             for (int m = 0; m < 4; ++m) {
;                 const int r = row0 + ai * HALF + m * 16;
;                 const float s = rs8[ai][m];
; #pragma unroll
;                 for (int bj = 0; bj < 2; ++bj) {
;                     f32x4 v0 = acc[ai][bj][m][0], v1 = acc[ai][bj][m][1];
;                     if (MODE == 2) { v0 = v0 * cs[bj][0]; v1 = v1 * cs[bj][1]; } else { v0 = v0 * s; v1 = v1 * s; }
;                     u32x4 w; w.x = pk2_(v0[0], v0[1]); w.y = pk2_(v0[2], v0[3]); w.z = pk2_(v1[0], v1[1]); w.w = pk2_(v1[2], v1[3]);
;                     *(PG8_GAS u32x4*)(O + (size_t)r * ldc + col0 + bj * HALF) = w;
;                 }
.LBB0_1462:
	s_lshl_b32 s8, s8, 8
	v_mov_b32_e32 v132, v252
	s_add_i32 s8, s8, s55
	s_mov_b32 s98, s55
	v_cmp_lt_i32_e32 vcc, v227, v226
	v_bfe_u32 v161, v132, 4, 2
	v_and_or_b32 v154, v132, 15, s8
	v_lshlrev_b32_e32 v132, 4, v161
	v_ashrrev_i32_e32 v155, 31, v154
	v_or_b32_e32 v150, 16, v154
	v_lshl_add_u64 v[186:187], s[16:17], 0, v[132:133]
	v_ashrrev_i32_e32 v151, 31, v150
	v_or_b32_e32 v152, 32, v154
	v_ashrrev_i32_e32 v153, 31, v152
	v_or_b32_e32 v146, 48, v154
	v_ashrrev_i32_e32 v147, 31, v146
	v_add_u32_e32 v148, 0x80, v154
	v_ashrrev_i32_e32 v149, 31, v148
	v_add_u32_e32 v142, 0x90, v154
	v_ashrrev_i32_e32 v143, 31, v142
	v_add_u32_e32 v144, 0xa0, v154
	v_add_u32_e32 v140, 0xb0, v154
	v_ashrrev_i32_e32 v145, 31, v144
	v_ashrrev_i32_e32 v141, 31, v140
	v_cndmask_b32_e32 v132, v253, v227, vcc
	v_lshlrev_b32_e32 v132, 2, v132
	v_xor_b32_e32 v156, 32, v253
	v_cmp_lt_i32_e32 vcc, v156, v226
	v_mov_b64_e32 v[194:195], s[30:31]
	s_nop 0
	v_cndmask_b32_e32 v156, v253, v156, vcc
	v_lshlrev_b32_e32 v156, 2, v156
	v_add_f32_e32 v240, v240, v241
	v_add_f32_e32 v242, v242, v243
	v_add_f32_e32 v244, v244, v245
	v_add_f32_e32 v246, v246, v247
	v_add_f32_e32 v240, v240, v242
	v_add_f32_e32 v244, v244, v246
	v_mov_b32_e32 v242, 0x358637bd
	s_nop 0
	v_add_f32_dpp v241, v240, v240 quad_perm:[1,0,3,2] row_mask:0xf bank_mask:0xf
	v_add_f32_dpp v245, v244, v244 quad_perm:[1,0,3,2] row_mask:0xf bank_mask:0xf
	v_and_b32_e32 v243, 60, v252
	v_lshl_add_u32 v243, v249, 7, v243
	v_add_f32_dpp v240, v241, v241 quad_perm:[2,3,0,1] row_mask:0xf bank_mask:0xf
	v_add_f32_dpp v244, v245, v245 quad_perm:[2,3,0,1] row_mask:0xf bank_mask:0xf
	v_add_u32_e32 v243, 0x21000, v243
	v_and_b32_e32 v246, 15, v252
	v_fmamk_f32 v240, v240, 0x3a800000, v242
	v_fmamk_f32 v244, v244, 0x3a800000, v242
	v_add_u32_e32 v246, s98, v246
	v_rsq_f32_e32 v240, v240
	v_rsq_f32_e32 v244, v244
	v_lshlrev_b32_e32 v246, 2, v246
	v_add_u32_e32 v246, 0x21000, v246
	ds_write_b32 v243, v240
	ds_write_b32 v243, v244 offset:64
	s_waitcnt lgkmcnt(0)
	s_barrier
	ds_read_b32 v162, v246
	ds_read_b32 v168, v246 offset:64
	ds_read_b32 v170, v246 offset:128
	ds_read_b32 v172, v246 offset:192
	ds_read_b32 v174, v246 offset:512
	ds_read_b32 v164, v246 offset:576
	ds_read_b32 v156, v246 offset:640
	ds_read_b32 v132, v246 offset:704
	s_waitcnt lgkmcnt(0)
	v_pk_mul_f32 v[108:109], v[108:109], v[168:169] op_sel_hi:[1,0]
	s_lshl_b32 s8, s61, 8
	v_lshl_or_b32 v161, v161, 3, s8
	v_or_b32_e32 v166, s56, v161
	v_pk_mul_f32 v[124:125], v[124:125], v[162:163] op_sel_hi:[1,0]
	v_pk_mul_f32 v[120:121], v[120:121], v[162:163] op_sel_hi:[1,0]
	v_ashrrev_i32_e32 v167, 31, v166
	v_pk_mul_f32 v[126:127], v[126:127], v[162:163] op_sel_hi:[1,0]
	v_pk_mul_f32 v[176:177], v[122:123], v[162:163] op_sel_hi:[1,0]
	v_cvt_pk_bf16_f32 v122, v124, v125
	v_cvt_pk_bf16_f32 v124, v120, v121
	v_lshlrev_b64 v[120:121], 11, v[154:155]
	v_cvt_pk_bf16_f32 v123, v126, v127
	v_lshl_add_u64 v[126:127], s[14:15], 0, v[120:121]
	v_lshlrev_b64 v[120:121], 1, v[166:167]
	v_cvt_pk_bf16_f32 v125, v176, v177
	v_lshl_add_u64 v[126:127], v[126:127], 0, v[120:121]
	global_store_dwordx4 v[126:127], v[122:125], off
	v_pk_mul_f32 v[114:115], v[114:115], v[162:163] op_sel_hi:[1,0]
	v_pk_mul_f32 v[112:113], v[112:113], v[162:163] op_sel_hi:[1,0]
	v_pk_mul_f32 v[122:123], v[106:107], v[162:163] op_sel_hi:[1,0]
	v_pk_mul_f32 v[106:107], v[104:105], v[162:163] op_sel_hi:[1,0]
	v_cvt_pk_bf16_f32 v104, v112, v113
	v_cvt_pk_bf16_f32 v105, v114, v115
	v_cvt_pk_bf16_f32 v106, v106, v107
	v_cvt_pk_bf16_f32 v107, v122, v123
	global_store_dwordx4 v[126:127], v[104:107], off offset:256
	v_pk_mul_f32 v[110:111], v[110:111], v[168:169] op_sel_hi:[1,0]
	v_pk_mul_f32 v[98:99], v[98:99], v[168:169] op_sel_hi:[1,0]
	v_pk_mul_f32 v[106:107], v[118:119], v[168:169] op_sel_hi:[1,0]
	v_pk_mul_f32 v[104:105], v[116:117], v[168:169] op_sel_hi:[1,0]
	v_pk_mul_f32 v[96:97], v[96:97], v[168:169] op_sel_hi:[1,0]
	v_cvt_pk_bf16_f32 v104, v104, v105
	v_cvt_pk_bf16_f32 v105, v106, v107
	v_cvt_pk_bf16_f32 v106, v108, v109
	v_lshlrev_b64 v[108:109], 11, v[150:151]
	v_lshl_add_u64 v[108:109], s[14:15], 0, v[108:109]
	v_cvt_pk_bf16_f32 v107, v110, v111
	v_lshl_add_u64 v[108:109], v[108:109], 0, v[120:121]
	global_store_dwordx4 v[108:109], v[104:107], off
	v_pk_mul_f32 v[92:93], v[92:93], v[170:171] op_sel_hi:[1,0]
	v_pk_mul_f32 v[94:95], v[94:95], v[170:171] op_sel_hi:[1,0]
	v_pk_mul_f32 v[104:105], v[90:91], v[168:169] op_sel_hi:[1,0]
	v_pk_mul_f32 v[90:91], v[88:89], v[168:169] op_sel_hi:[1,0]
	v_cvt_pk_bf16_f32 v88, v96, v97
	v_cvt_pk_bf16_f32 v89, v98, v99
	v_cvt_pk_bf16_f32 v90, v90, v91
	v_cvt_pk_bf16_f32 v91, v104, v105
	global_store_dwordx4 v[108:109], v[88:91], off offset:256
	v_pk_mul_f32 v[82:83], v[82:83], v[170:171] op_sel_hi:[1,0]
	v_pk_mul_f32 v[80:81], v[80:81], v[170:171] op_sel_hi:[1,0]
	v_pk_mul_f32 v[90:91], v[102:103], v[170:171] op_sel_hi:[1,0]
	v_pk_mul_f32 v[88:89], v[100:101], v[170:171] op_sel_hi:[1,0]
	v_pk_mul_f32 v[76:77], v[76:77], v[172:173] op_sel_hi:[1,0]
	v_cvt_pk_bf16_f32 v88, v88, v89
	v_cvt_pk_bf16_f32 v89, v90, v91
	v_cvt_pk_bf16_f32 v90, v92, v93
	v_lshlrev_b64 v[92:93], 11, v[152:153]
	v_lshl_add_u64 v[92:93], s[14:15], 0, v[92:93]
	v_cvt_pk_bf16_f32 v91, v94, v95
	v_lshl_add_u64 v[92:93], v[92:93], 0, v[120:121]
	global_store_dwordx4 v[92:93], v[88:91], off
; #define PG8_GAS __attribute__((address_space(1)))
; __device__ __forceinline__ unsigned pk2_(float lo, float hi) { f32x2c_t v = {lo, hi}; bf16x2c_t b = __builtin_convertvector(v, bf16x2c_t); return __builtin_bit_cast(unsigned, b); }
;     __device__ __forceinline__ void operator()(const f32x4 (&acc)[2][2][4][2], const Unit& u, int wr, int wc, int fr, int fq) const {
;     ...
; #pragma unroll
;         for (int ai = 0; ai < 2; ++ai)
; #pragma unroll
;             for (int m = 0; m < 4; ++m) {
;                 const int r = row0 + ai * HALF + m * 16;
;                 const float s = rs8[ai][m];
; #pragma unroll
;                 for (int bj = 0; bj < 2; ++bj) {
;                     f32x4 v0 = acc[ai][bj][m][0], v1 = acc[ai][bj][m][1];
;                     if (MODE == 2) { v0 = v0 * cs[bj][0]; v1 = v1 * cs[bj][1]; } else { v0 = v0 * s; v1 = v1 * s; }
;                     u32x4 w; w.x = pk2_(v0[0], v0[1]); w.y = pk2_(v0[2], v0[3]); w.z = pk2_(v1[0], v1[1]); w.w = pk2_(v1[2], v1[3]);
;                     *(PG8_GAS u32x4*)(O + (size_t)r * ldc + col0 + bj * HALF) = w;
;                 }
;             }
	v_pk_mul_f32 v[78:79], v[78:79], v[172:173] op_sel_hi:[1,0]
	v_pk_mul_f32 v[70:71], v[70:71], v[172:173] op_sel_hi:[1,0]
	v_pk_mul_f32 v[88:89], v[74:75], v[170:171] op_sel_hi:[1,0]
	v_pk_mul_f32 v[74:75], v[72:73], v[170:171] op_sel_hi:[1,0]
	v_cvt_pk_bf16_f32 v72, v80, v81
	v_cvt_pk_bf16_f32 v73, v82, v83
	v_cvt_pk_bf16_f32 v74, v74, v75
	v_cvt_pk_bf16_f32 v75, v88, v89
	global_store_dwordx4 v[92:93], v[72:75], off offset:256
	v_pk_mul_f32 v[68:69], v[68:69], v[172:173] op_sel_hi:[1,0]
	v_pk_mul_f32 v[60:61], v[60:61], v[174:175] op_sel_hi:[1,0]
	v_pk_mul_f32 v[74:75], v[86:87], v[172:173] op_sel_hi:[1,0]
	v_pk_mul_f32 v[72:73], v[84:85], v[172:173] op_sel_hi:[1,0]
	v_pk_mul_f32 v[62:63], v[62:63], v[174:175] op_sel_hi:[1,0]
	v_cvt_pk_bf16_f32 v72, v72, v73
	v_cvt_pk_bf16_f32 v73, v74, v75
	v_cvt_pk_bf16_f32 v74, v76, v77
	v_lshlrev_b64 v[76:77], 11, v[146:147]
	v_lshl_add_u64 v[76:77], s[14:15], 0, v[76:77]
	v_cvt_pk_bf16_f32 v75, v78, v79
	v_lshl_add_u64 v[76:77], v[76:77], 0, v[120:121]
	global_store_dwordx4 v[76:77], v[72:75], off
	v_pk_mul_f32 v[50:51], v[50:51], v[174:175] op_sel_hi:[1,0]
	v_pk_mul_f32 v[48:49], v[48:49], v[174:175] op_sel_hi:[1,0]
	v_pk_mul_f32 v[72:73], v[66:67], v[172:173] op_sel_hi:[1,0]
	v_pk_mul_f32 v[66:67], v[64:65], v[172:173] op_sel_hi:[1,0]
	v_cvt_pk_bf16_f32 v64, v68, v69
	v_cvt_pk_bf16_f32 v65, v70, v71
	v_cvt_pk_bf16_f32 v66, v66, v67
	v_cvt_pk_bf16_f32 v67, v72, v73
	global_store_dwordx4 v[76:77], v[64:67], off offset:256
	v_pk_mul_f32 v[44:45], v[44:45], v[164:165] op_sel_hi:[1,0]
	v_pk_mul_f32 v[46:47], v[46:47], v[164:165] op_sel_hi:[1,0]
	v_pk_mul_f32 v[64:65], v[58:59], v[174:175] op_sel_hi:[1,0]
	v_pk_mul_f32 v[58:59], v[56:57], v[174:175] op_sel_hi:[1,0]
	v_cvt_pk_bf16_f32 v56, v60, v61
	v_lshlrev_b64 v[60:61], 11, v[148:149]
	v_lshl_add_u64 v[60:61], s[14:15], 0, v[60:61]
	v_cvt_pk_bf16_f32 v57, v62, v63
	v_cvt_pk_bf16_f32 v58, v58, v59
	v_cvt_pk_bf16_f32 v59, v64, v65
	v_lshl_add_u64 v[60:61], v[60:61], 0, v[120:121]
	global_store_dwordx4 v[60:61], v[56:59], off
	v_pk_mul_f32 v[34:35], v[34:35], v[164:165] op_sel_hi:[1,0]
	v_pk_mul_f32 v[32:33], v[32:33], v[164:165] op_sel_hi:[1,0]
	v_pk_mul_f32 v[56:57], v[42:43], v[174:175] op_sel_hi:[1,0]
	v_pk_mul_f32 v[42:43], v[40:41], v[174:175] op_sel_hi:[1,0]
	v_cvt_pk_bf16_f32 v40, v48, v49
	v_cvt_pk_bf16_f32 v41, v50, v51
	v_cvt_pk_bf16_f32 v42, v42, v43
	v_cvt_pk_bf16_f32 v43, v56, v57
	global_store_dwordx4 v[60:61], v[40:43], off offset:256
	v_pk_mul_f32 v[28:29], v[28:29], v[156:157] op_sel_hi:[1,0]
	v_pk_mul_f32 v[30:31], v[30:31], v[156:157] op_sel_hi:[1,0]
	v_pk_mul_f32 v[42:43], v[54:55], v[164:165] op_sel_hi:[1,0]
	v_pk_mul_f32 v[40:41], v[52:53], v[164:165] op_sel_hi:[1,0]
	v_pk_mul_f32 v[18:19], v[18:19], v[156:157] op_sel_hi:[1,0]
	v_cvt_pk_bf16_f32 v40, v40, v41
	v_cvt_pk_bf16_f32 v41, v42, v43
	v_cvt_pk_bf16_f32 v42, v44, v45
	v_lshlrev_b64 v[44:45], 11, v[142:143]
	v_lshl_add_u64 v[44:45], s[14:15], 0, v[44:45]
	v_cvt_pk_bf16_f32 v43, v46, v47
	v_lshl_add_u64 v[44:45], v[44:45], 0, v[120:121]
	global_store_dwordx4 v[44:45], v[40:43], off
	v_pk_mul_f32 v[16:17], v[16:17], v[156:157] op_sel_hi:[1,0]
	v_pk_mul_f32 v[12:13], v[12:13], v[132:133] op_sel_hi:[1,0]
	v_pk_mul_f32 v[40:41], v[26:27], v[164:165] op_sel_hi:[1,0]
	v_pk_mul_f32 v[26:27], v[24:25], v[164:165] op_sel_hi:[1,0]
	v_cvt_pk_bf16_f32 v24, v32, v33
	v_cvt_pk_bf16_f32 v25, v34, v35
	v_cvt_pk_bf16_f32 v26, v26, v27
	v_cvt_pk_bf16_f32 v27, v40, v41
	global_store_dwordx4 v[44:45], v[24:27], off offset:256
	v_pk_mul_f32 v[14:15], v[14:15], v[132:133] op_sel_hi:[1,0]
	v_pk_mul_f32 v[6:7], v[6:7], v[132:133] op_sel_hi:[1,0]
	v_pk_mul_f32 v[26:27], v[38:39], v[156:157] op_sel_hi:[1,0]
	v_pk_mul_f32 v[24:25], v[36:37], v[156:157] op_sel_hi:[1,0]
	v_pk_mul_f32 v[4:5], v[4:5], v[132:133] op_sel_hi:[1,0]
	v_cvt_pk_bf16_f32 v24, v24, v25
	v_cvt_pk_bf16_f32 v25, v26, v27
	v_cvt_pk_bf16_f32 v26, v28, v29
	v_lshlrev_b64 v[28:29], 11, v[144:145]
	v_lshl_add_u64 v[28:29], s[14:15], 0, v[28:29]
	v_cvt_pk_bf16_f32 v27, v30, v31
	v_lshl_add_u64 v[28:29], v[28:29], 0, v[120:121]
	global_store_dwordx4 v[28:29], v[24:27], off
	s_andn2_b64 vcc, exec, s[6:7]
	s_mov_b64 s[6:7], -1
	v_pk_mul_f32 v[24:25], v[10:11], v[156:157] op_sel_hi:[1,0]
	v_pk_mul_f32 v[10:11], v[8:9], v[156:157] op_sel_hi:[1,0]
	v_cvt_pk_bf16_f32 v8, v16, v17
	v_cvt_pk_bf16_f32 v9, v18, v19
	v_cvt_pk_bf16_f32 v10, v10, v11
	v_cvt_pk_bf16_f32 v11, v24, v25
	global_store_dwordx4 v[28:29], v[8:11], off offset:256
	s_nop 1
	v_pk_mul_f32 v[10:11], v[22:23], v[132:133] op_sel_hi:[1,0]
	v_pk_mul_f32 v[8:9], v[20:21], v[132:133] op_sel_hi:[1,0]
	s_nop 0
	v_cvt_pk_bf16_f32 v8, v8, v9
	v_cvt_pk_bf16_f32 v9, v10, v11
	v_cvt_pk_bf16_f32 v10, v12, v13
	v_lshlrev_b64 v[12:13], 11, v[140:141]
	v_lshl_add_u64 v[12:13], s[14:15], 0, v[12:13]
	v_cvt_pk_bf16_f32 v11, v14, v15
	v_lshl_add_u64 v[12:13], v[12:13], 0, v[120:121]
	global_store_dwordx4 v[12:13], v[8:11], off
	s_nop 1
	v_pk_mul_f32 v[8:9], v[2:3], v[132:133] op_sel_hi:[1,0]
	v_pk_mul_f32 v[2:3], v[0:1], v[132:133] op_sel_hi:[1,0]
	v_cvt_pk_bf16_f32 v0, v4, v5
	v_cvt_pk_bf16_f32 v1, v6, v7
	v_cvt_pk_bf16_f32 v2, v2, v3
	v_cvt_pk_bf16_f32 v3, v8, v9
	global_store_dwordx4 v[12:13], v[0:3], off offset:256
	s_cbranch_vccnz .LBB0_1451
	s_andn2_b64 vcc, exec, s[12:13]
	s_cbranch_vccnz .LBB0_1450
	s_barrier
	s_branch .LBB0_1450

; #define PG8_GAS __attribute__((address_space(1)))
;     __device__ bool next(int i, Unit& u) const { const long L = (long)i * G + c0; if (L >= n) return false; u.pm = (int)L / nN; u.pn = (int)L % nN; return true; }
;     __host__ __device__ bool next(int i, Unit& u) const {
;         const long L = (long)i * G + c; if (L >= nwg) return false;
;         int wgid = (int)L; { const int q = nwg / NXCD, r = nwg % NXCD, xcd = wgid % NXCD, off = wgid / NXCD; wgid = (xcd < r ? xcd * (q + 1) : r * (q + 1) + (xcd - r) * q) + off; }
;         const int nig = WGM * nN, gid = wgid / nig, fm = gid * WGM, gsz = (nM - fm) < WGM ? (nM - fm) : WGM;
;         u.pm = fm + ((wgid % nig) % gsz); u.pn = (wgid % nig) / gsz; return true;
; __device__ __forceinline__ float row_rstd(const float* parts, int r, int fq) {
;     const f32x4 p = *(const PG8_GAS f32x4*)(parts + (size_t)r * 16 + 4 * fq);
.LBB0_1655:
	s_lshl_b32 s99, s8, 8
	s_lshl_b32 s100, s99, 6
	s_add_u32 s100, s16, s100
	s_addc_u32 s101, s17, 0
	v_lshrrev_b32_e32 v249, 6, v252
	v_and_b32_e32 v248, 63, v252
	v_lshlrev_b32_e32 v248, 4, v248
	v_lshl_or_b32 v248, v249, 11, v248
	global_load_dwordx4 v[240:243], v248, s[100:101]
	global_load_dwordx4 v[244:247], v248, s[100:101] offset:1024
	s_add_i32 s53, s53, 1
	s_mul_i32 s6, s53, s58
	s_mul_hi_u32 s7, s53, s76
	s_add_i32 s7, s7, s6
	s_mul_i32 s6, s53, s76
	s_add_u32 s38, s6, s77
	s_addc_u32 s39, s7, s47
	v_cmp_gt_i64_e32 vcc, s[38:39], v[138:139]
	v_cmp_lt_i64_e64 s[6:7], s[38:39], v[136:137]
	s_cbranch_vccnz .LBB0_1657
	s_ashr_i32 s9, s38, 31
	s_lshr_b32 s9, s9, 29
	s_add_i32 s9, s38, s9
	s_ashr_i32 s33, s9, 3
	s_and_b32 s9, s9, -8
	s_sub_i32 s9, s38, s9
	s_cmp_lt_i32 s9, 0
	s_cselect_b32 s34, s48, 0x160
	s_mul_i32 s9, s9, s34
	s_add_i32 s9, s9, s33
	s_mul_hi_i32 s33, s9, 0x2e8ba2e9
	s_lshr_b32 s34, s33, 31
	s_ashr_i32 s33, s33, 5
	s_add_i32 s33, s33, s34
	s_lshl_b32 s35, s33, 3
	s_sub_i32 s34, 0x80, s35
	s_min_i32 s36, s34, 8
	s_abs_i32 s34, s36
	v_cvt_f32_u32_e32 v0, s34
	s_sub_i32 s38, 0, s34
	s_mulk_i32 s33, 0xb0
	s_sub_i32 s9, s9, s33
	v_rcp_iflag_f32_e32 v0, v0
	s_abs_i32 s33, s9
	s_xor_b32 s37, s9, s36
	s_ashr_i32 s37, s37, 31
	v_mul_f32_e32 v0, 0x4f7ffffe, v0
	v_cvt_u32_f32_e32 v0, v0
	s_nop 0
	v_readfirstlane_b32 s39, v0
	s_mul_i32 s38, s38, s39
	s_mul_hi_u32 s38, s39, s38
	s_add_i32 s39, s39, s38
	s_mul_hi_u32 s38, s33, s39
	s_mul_i32 s39, s38, s34
	s_sub_i32 s33, s33, s39
	s_add_i32 s40, s38, 1
	s_sub_i32 s39, s33, s34
	s_cmp_ge_u32 s33, s34
	s_cselect_b32 s38, s40, s38
	s_cselect_b32 s33, s39, s33
	s_add_i32 s39, s38, 1
	s_cmp_ge_u32 s33, s34
	s_cselect_b32 s33, s39, s38
	s_xor_b32 s33, s33, s37
	s_sub_i32 s34, s33, s37
	s_mul_i32 s33, s34, s36
	s_sub_i32 s9, s9, s33
	s_add_i32 s36, s35, s9

; #define PG8_GAS __attribute__((address_space(1)))
; __device__ __forceinline__ unsigned pk2_(float lo, float hi) { f32x2c_t v = {lo, hi}; bf16x2c_t b = __builtin_convertvector(v, bf16x2c_t); return __builtin_bit_cast(unsigned, b); }
; __device__ __forceinline__ float silu_f(float x) { return x * __builtin_amdgcn_rcpf(1.0f + __builtin_amdgcn_exp2f(-1.4426950408889634f * x)); }
; __device__ __forceinline__ float row_rstd(const float* parts, int r, int fq) {
;     const f32x4 p = *(const PG8_GAS f32x4*)(parts + (size_t)r * 16 + 4 * fq);
;     float s = (p[0] + p[1]) + (p[2] + p[3]);
;     s += __shfl_xor(s, 16); s += __shfl_xor(s, 32);
;     return rsqrtf(s * (1.0f / 1024.0f) + RMS_EPS);
; }
;     __device__ __forceinline__ void operator()(const f32x4 (&acc)[2][2][4][2], const Unit& u, int wr, int wc, int fr, int fq) const {
;         const int row0 = u.pm * BM + wr * 64 + fr, col0 = u.pn * 128 + wc * 32 + 8 * fq;
;         float rs8[2][4];
; #pragma unroll
;         for (int ai = 0; ai < 2; ++ai)
; #pragma unroll
;             for (int m = 0; m < 4; ++m) rs8[ai][m] = row_rstd(parts, row0 + ai * HALF + m * 16, fq);
; #pragma unroll
;         for (int ai = 0; ai < 2; ++ai)
; #pragma unroll
;             for (int m = 0; m < 4; ++m) {
;                 const int r = row0 + ai * HALF + m * 16; const float s = rs8[ai][m];
;                 float o[8];
; #pragma unroll
;                 for (int n = 0; n < 2; ++n)
; #pragma unroll
;                     for (int i = 0; i < 4; ++i) o[4 * n + i] = silu_f(acc[ai][0][m][n][i] * s) * (acc[ai][1][m][n][i] * s);
;                 u32x4 w; w.x = pk2_(o[0], o[1]); w.y = pk2_(o[2], o[3]); w.z = pk2_(o[4], o[5]); w.w = pk2_(o[6], o[7]);
;                 *(PG8_GAS u32x4*)(O + (size_t)r * 2816 + col0) = w;
.LBB0_1661:
	s_lshl_b32 s8, s8, 8
	v_mov_b32_e32 v132, v252
	s_add_i32 s8, s8, s56
	s_mov_b32 s98, s56
	v_cmp_lt_i32_e32 vcc, v227, v226
	v_bfe_u32 v200, v132, 4, 2
	v_and_or_b32 v160, v132, 15, s8
	v_lshlrev_b32_e32 v132, 4, v200
	v_ashrrev_i32_e32 v161, 31, v160
	v_or_b32_e32 v156, 16, v160
	v_lshl_add_u64 v[188:189], s[16:17], 0, v[132:133]
	v_ashrrev_i32_e32 v157, 31, v156
	v_or_b32_e32 v152, 32, v160
	v_ashrrev_i32_e32 v153, 31, v152
	v_or_b32_e32 v150, 48, v160
	v_ashrrev_i32_e32 v151, 31, v150
	v_add_u32_e32 v146, 0x80, v160
	v_ashrrev_i32_e32 v147, 31, v146
	v_add_u32_e32 v144, 0x90, v160
	v_ashrrev_i32_e32 v145, 31, v144
	v_add_u32_e32 v142, 0xa0, v160
	v_add_u32_e32 v140, 0xb0, v160
	v_cndmask_b32_e32 v132, v253, v227, vcc
	v_lshlrev_b32_e32 v132, 2, v132
	v_xor_b32_e32 v145, 32, v253
	v_cmp_lt_i32_e32 vcc, v145, v226
	v_mov_b64_e32 v[196:197], s[30:31]
	v_add_f32_e32 v240, v240, v241
	v_add_f32_e32 v242, v242, v243
	v_add_f32_e32 v244, v244, v245
	v_add_f32_e32 v246, v246, v247
	v_add_f32_e32 v240, v240, v242
	v_add_f32_e32 v244, v244, v246
	v_mov_b32_e32 v242, 0x358637bd
	s_nop 0
	v_add_f32_dpp v241, v240, v240 quad_perm:[1,0,3,2] row_mask:0xf bank_mask:0xf
	v_add_f32_dpp v245, v244, v244 quad_perm:[1,0,3,2] row_mask:0xf bank_mask:0xf
	v_and_b32_e32 v243, 60, v252
	v_lshl_add_u32 v243, v249, 7, v243
	v_add_f32_dpp v240, v241, v241 quad_perm:[2,3,0,1] row_mask:0xf bank_mask:0xf
	v_add_f32_dpp v244, v245, v245 quad_perm:[2,3,0,1] row_mask:0xf bank_mask:0xf
	v_add_u32_e32 v243, 0x21000, v243
	v_and_b32_e32 v246, 15, v252
	v_fmamk_f32 v240, v240, 0x3a800000, v242
	v_fmamk_f32 v244, v244, 0x3a800000, v242
	v_add_u32_e32 v246, s98, v246
	v_rsq_f32_e32 v240, v240
	v_rsq_f32_e32 v244, v244
	v_lshlrev_b32_e32 v246, 2, v246
	v_add_u32_e32 v246, 0x21000, v246
	ds_write_b32 v243, v240
	ds_write_b32 v243, v244 offset:64
	s_waitcnt lgkmcnt(0)
	s_barrier
	ds_read_b32 v168, v246
	ds_read_b32 v172, v246 offset:64
	ds_read_b32 v164, v246 offset:128
	ds_read_b32 v162, v246 offset:192
	ds_read_b32 v158, v246 offset:512
	ds_read_b32 v154, v246 offset:576
	ds_read_b32 v148, v246 offset:640
	ds_read_b32 v132, v246 offset:704
	s_waitcnt lgkmcnt(0)
	s_lshl_b32 s8, s63, 7
	v_lshl_or_b32 v141, v200, 3, s8
	v_pk_mul_f32 v[124:125], v[124:125], v[168:169] op_sel_hi:[1,0]
	v_or_b32_e32 v166, s57, v141
	v_mul_f32_e32 v141, 0xbfb8aa3b, v124
	v_exp_f32_e32 v141, v141
	v_mul_f32_e32 v143, 0xbfb8aa3b, v125
	v_exp_f32_e32 v143, v143
	v_pk_mul_f32 v[126:127], v[126:127], v[168:169] op_sel_hi:[1,0]
	v_add_f32_e32 v141, 1.0, v141
	v_rcp_f32_e32 v170, v141
	v_add_f32_e32 v141, 1.0, v143
	v_mul_f32_e32 v143, 0xbfb8aa3b, v126
	v_exp_f32_e32 v143, v143
	v_mul_f32_e32 v145, 0xbfb8aa3b, v127
	v_exp_f32_e32 v145, v145
	v_rcp_f32_e32 v171, v141
	v_add_f32_e32 v141, 1.0, v143
	v_rcp_f32_e32 v174, v141
	v_add_f32_e32 v141, 1.0, v145
	v_rcp_f32_e32 v175, v141
	v_pk_mul_f32 v[124:125], v[124:125], v[170:171]
	v_pk_mul_f32 v[116:117], v[116:117], v[168:169] op_sel_hi:[1,0]
	v_pk_mul_f32 v[120:121], v[120:121], v[168:169] op_sel_hi:[1,0]
	v_pk_mul_f32 v[116:117], v[116:117], v[124:125]
	v_pk_mul_f32 v[124:125], v[126:127], v[174:175]
	v_mul_f32_e32 v126, 0xbfb8aa3b, v120
	v_mul_f32_e32 v127, 0xbfb8aa3b, v121
	v_exp_f32_e32 v126, v126
	v_exp_f32_e32 v127, v127
	v_pk_mul_f32 v[118:119], v[118:119], v[168:169] op_sel_hi:[1,0]
	v_pk_mul_f32 v[122:123], v[122:123], v[168:169] op_sel_hi:[1,0]
	v_pk_mul_f32 v[118:119], v[118:119], v[124:125]
	v_add_f32_e32 v124, 1.0, v126
	v_add_f32_e32 v125, 1.0, v127
	v_mul_f32_e32 v126, 0xbfb8aa3b, v122
	v_mul_f32_e32 v127, 0xbfb8aa3b, v123
	v_exp_f32_e32 v126, v126
	v_exp_f32_e32 v127, v127
	v_rcp_f32_e32 v124, v124
	v_rcp_f32_e32 v125, v125
	v_add_f32_e32 v126, 1.0, v126
	v_add_f32_e32 v127, 1.0, v127
	v_rcp_f32_e32 v126, v126
	v_rcp_f32_e32 v127, v127
	v_pk_mul_f32 v[120:121], v[120:121], v[124:125]
	v_pk_mul_f32 v[112:113], v[112:113], v[168:169] op_sel_hi:[1,0]
	v_pk_mul_f32 v[114:115], v[114:115], v[168:169] op_sel_hi:[1,0]
	v_pk_mul_f32 v[112:113], v[112:113], v[120:121]
	v_pk_mul_f32 v[120:121], v[122:123], v[126:127]
	v_ashrrev_i32_e32 v167, 31, v166
	v_pk_mul_f32 v[114:115], v[114:115], v[120:121]
	v_cvt_pk_bf16_f32 v116, v116, v117
	v_cvt_pk_bf16_f32 v117, v118, v119
	v_cvt_pk_bf16_f32 v118, v112, v113
	v_mov_b64_e32 v[112:113], s[14:15]
	v_cvt_pk_bf16_f32 v119, v114, v115
	v_mad_i64_i32 v[120:121], s[8:9], v160, s62, v[112:113]
	v_lshlrev_b64 v[114:115], 1, v[166:167]
	v_pk_mul_f32 v[108:109], v[108:109], v[172:173] op_sel_hi:[1,0]
	v_lshl_add_u64 v[120:121], v[120:121], 0, v[114:115]
	v_mul_f32_e32 v122, 0xbfb8aa3b, v108
	v_mul_f32_e32 v123, 0xbfb8aa3b, v109
	v_pk_mul_f32 v[110:111], v[110:111], v[172:173] op_sel_hi:[1,0]
	v_exp_f32_e32 v122, v122
	v_exp_f32_e32 v123, v123
	global_store_dwordx4 v[120:121], v[116:119], off
	v_pk_mul_f32 v[100:101], v[100:101], v[172:173] op_sel_hi:[1,0]
	v_pk_mul_f32 v[104:105], v[104:105], v[172:173] op_sel_hi:[1,0]
	v_mul_f32_e32 v118, 0xbfb8aa3b, v110
	v_mul_f32_e32 v119, 0xbfb8aa3b, v111
	v_exp_f32_e32 v118, v118
	v_exp_f32_e32 v119, v119
	v_add_f32_e32 v116, 1.0, v122
	v_add_f32_e32 v117, 1.0, v123
	v_rcp_f32_e32 v116, v116
	v_rcp_f32_e32 v117, v117
	v_add_f32_e32 v118, 1.0, v118
	v_add_f32_e32 v119, 1.0, v119
	v_rcp_f32_e32 v118, v118
	v_rcp_f32_e32 v119, v119
	v_pk_mul_f32 v[108:109], v[108:109], v[116:117]
	v_pk_mul_f32 v[102:103], v[102:103], v[172:173] op_sel_hi:[1,0]
	v_pk_mul_f32 v[100:101], v[100:101], v[108:109]
	v_pk_mul_f32 v[108:109], v[110:111], v[118:119]
	v_mul_f32_e32 v110, 0xbfb8aa3b, v104
	v_mul_f32_e32 v111, 0xbfb8aa3b, v105
	v_exp_f32_e32 v110, v110
	v_exp_f32_e32 v111, v111
; #define PG8_GAS __attribute__((address_space(1)))
; __device__ __forceinline__ unsigned pk2_(float lo, float hi) { f32x2c_t v = {lo, hi}; bf16x2c_t b = __builtin_convertvector(v, bf16x2c_t); return __builtin_bit_cast(unsigned, b); }
; __device__ __forceinline__ float silu_f(float x) { return x * __builtin_amdgcn_rcpf(1.0f + __builtin_amdgcn_exp2f(-1.4426950408889634f * x)); }
;     __device__ __forceinline__ void operator()(const f32x4 (&acc)[2][2][4][2], const Unit& u, int wr, int wc, int fr, int fq) const {
;     ...
;             for (int m = 0; m < 4; ++m) {
;                 const int r = row0 + ai * HALF + m * 16; const float s = rs8[ai][m];
;                 float o[8];
; #pragma unroll
;                 for (int n = 0; n < 2; ++n)
; #pragma unroll
;                     for (int i = 0; i < 4; ++i) o[4 * n + i] = silu_f(acc[ai][0][m][n][i] * s) * (acc[ai][1][m][n][i] * s);
;                 u32x4 w; w.x = pk2_(o[0], o[1]); w.y = pk2_(o[2], o[3]); w.z = pk2_(o[4], o[5]); w.w = pk2_(o[6], o[7]);
;                 *(PG8_GAS u32x4*)(O + (size_t)r * 2816 + col0) = w;
;             }
	v_pk_mul_f32 v[106:107], v[106:107], v[172:173] op_sel_hi:[1,0]
	v_pk_mul_f32 v[102:103], v[102:103], v[108:109]
	v_add_f32_e32 v108, 1.0, v110
	v_add_f32_e32 v109, 1.0, v111
	v_mul_f32_e32 v110, 0xbfb8aa3b, v106
	v_mul_f32_e32 v111, 0xbfb8aa3b, v107
	v_exp_f32_e32 v110, v110
	v_exp_f32_e32 v111, v111
	v_rcp_f32_e32 v108, v108
	v_rcp_f32_e32 v109, v109
	v_add_f32_e32 v110, 1.0, v110
	v_add_f32_e32 v111, 1.0, v111
	v_rcp_f32_e32 v110, v110
	v_rcp_f32_e32 v111, v111
	v_pk_mul_f32 v[104:105], v[104:105], v[108:109]
	v_pk_mul_f32 v[96:97], v[96:97], v[172:173] op_sel_hi:[1,0]
	v_pk_mul_f32 v[98:99], v[98:99], v[172:173] op_sel_hi:[1,0]
	v_pk_mul_f32 v[104:105], v[96:97], v[104:105]
	v_pk_mul_f32 v[96:97], v[106:107], v[110:111]
	v_pk_mul_f32 v[92:93], v[92:93], v[164:165] op_sel_hi:[1,0]
	v_pk_mul_f32 v[106:107], v[98:99], v[96:97]
	v_cvt_pk_bf16_f32 v96, v100, v101
	v_mad_i64_i32 v[100:101], s[8:9], v156, s62, v[112:113]
	v_cvt_pk_bf16_f32 v97, v102, v103
	v_cvt_pk_bf16_f32 v98, v104, v105
	v_cvt_pk_bf16_f32 v99, v106, v107
	v_lshl_add_u64 v[100:101], v[100:101], 0, v[114:115]
	v_mul_f32_e32 v102, 0xbfb8aa3b, v92
	v_mul_f32_e32 v103, 0xbfb8aa3b, v93
	v_pk_mul_f32 v[94:95], v[94:95], v[164:165] op_sel_hi:[1,0]
	v_exp_f32_e32 v102, v102
	v_exp_f32_e32 v103, v103
	global_store_dwordx4 v[100:101], v[96:99], off
	v_pk_mul_f32 v[84:85], v[84:85], v[164:165] op_sel_hi:[1,0]
	v_pk_mul_f32 v[88:89], v[88:89], v[164:165] op_sel_hi:[1,0]
	v_mul_f32_e32 v98, 0xbfb8aa3b, v94
	v_mul_f32_e32 v99, 0xbfb8aa3b, v95
	v_exp_f32_e32 v98, v98
	v_exp_f32_e32 v99, v99
	v_add_f32_e32 v96, 1.0, v102
	v_add_f32_e32 v97, 1.0, v103
	v_rcp_f32_e32 v96, v96
	v_rcp_f32_e32 v97, v97
	v_add_f32_e32 v98, 1.0, v98
	v_add_f32_e32 v99, 1.0, v99
	v_rcp_f32_e32 v98, v98
	v_rcp_f32_e32 v99, v99
	v_pk_mul_f32 v[92:93], v[92:93], v[96:97]
	v_pk_mul_f32 v[86:87], v[86:87], v[164:165] op_sel_hi:[1,0]
	v_pk_mul_f32 v[84:85], v[84:85], v[92:93]
	v_pk_mul_f32 v[92:93], v[94:95], v[98:99]
	v_mul_f32_e32 v94, 0xbfb8aa3b, v88
	v_mul_f32_e32 v95, 0xbfb8aa3b, v89
	v_exp_f32_e32 v94, v94
	v_exp_f32_e32 v95, v95
	v_pk_mul_f32 v[90:91], v[90:91], v[164:165] op_sel_hi:[1,0]
	v_pk_mul_f32 v[86:87], v[86:87], v[92:93]
	v_add_f32_e32 v92, 1.0, v94
	v_add_f32_e32 v93, 1.0, v95
	v_mul_f32_e32 v94, 0xbfb8aa3b, v90
	v_mul_f32_e32 v95, 0xbfb8aa3b, v91
	v_exp_f32_e32 v94, v94
	v_exp_f32_e32 v95, v95
	v_rcp_f32_e32 v92, v92
	v_rcp_f32_e32 v93, v93
	v_add_f32_e32 v94, 1.0, v94
	v_add_f32_e32 v95, 1.0, v95
	v_rcp_f32_e32 v94, v94
	v_rcp_f32_e32 v95, v95
	v_pk_mul_f32 v[88:89], v[88:89], v[92:93]
	v_pk_mul_f32 v[80:81], v[80:81], v[164:165] op_sel_hi:[1,0]
	v_pk_mul_f32 v[82:83], v[82:83], v[164:165] op_sel_hi:[1,0]
	v_pk_mul_f32 v[88:89], v[80:81], v[88:89]
	v_pk_mul_f32 v[80:81], v[90:91], v[94:95]
	v_pk_mul_f32 v[76:77], v[76:77], v[162:163] op_sel_hi:[1,0]
	v_pk_mul_f32 v[90:91], v[82:83], v[80:81]
	v_cvt_pk_bf16_f32 v80, v84, v85
	v_mad_i64_i32 v[84:85], s[8:9], v152, s62, v[112:113]
	v_cvt_pk_bf16_f32 v81, v86, v87
	v_cvt_pk_bf16_f32 v82, v88, v89
	v_cvt_pk_bf16_f32 v83, v90, v91
	v_lshl_add_u64 v[84:85], v[84:85], 0, v[114:115]
	v_mul_f32_e32 v86, 0xbfb8aa3b, v76
	v_mul_f32_e32 v87, 0xbfb8aa3b, v77
	v_pk_mul_f32 v[78:79], v[78:79], v[162:163] op_sel_hi:[1,0]
	v_exp_f32_e32 v86, v86
	v_exp_f32_e32 v87, v87
	global_store_dwordx4 v[84:85], v[80:83], off
	v_pk_mul_f32 v[68:69], v[68:69], v[162:163] op_sel_hi:[1,0]
	v_pk_mul_f32 v[72:73], v[72:73], v[162:163] op_sel_hi:[1,0]
	v_mul_f32_e32 v82, 0xbfb8aa3b, v78
	v_mul_f32_e32 v83, 0xbfb8aa3b, v79
	v_exp_f32_e32 v82, v82
	v_exp_f32_e32 v83, v83
	v_add_f32_e32 v80, 1.0, v86
	v_add_f32_e32 v81, 1.0, v87
	v_rcp_f32_e32 v80, v80
	v_rcp_f32_e32 v81, v81
	v_add_f32_e32 v82, 1.0, v82
	v_add_f32_e32 v83, 1.0, v83
	v_rcp_f32_e32 v82, v82
	v_rcp_f32_e32 v83, v83
	v_pk_mul_f32 v[76:77], v[76:77], v[80:81]
	v_pk_mul_f32 v[70:71], v[70:71], v[162:163] op_sel_hi:[1,0]
	v_pk_mul_f32 v[68:69], v[68:69], v[76:77]
	v_pk_mul_f32 v[76:77], v[78:79], v[82:83]
	v_mul_f32_e32 v78, 0xbfb8aa3b, v72
	v_mul_f32_e32 v79, 0xbfb8aa3b, v73
	v_exp_f32_e32 v78, v78
	v_exp_f32_e32 v79, v79
	v_pk_mul_f32 v[74:75], v[74:75], v[162:163] op_sel_hi:[1,0]
	v_pk_mul_f32 v[70:71], v[70:71], v[76:77]
	v_add_f32_e32 v76, 1.0, v78
	v_add_f32_e32 v77, 1.0, v79
	v_mul_f32_e32 v78, 0xbfb8aa3b, v74
	v_mul_f32_e32 v79, 0xbfb8aa3b, v75
	v_exp_f32_e32 v78, v78
	v_exp_f32_e32 v79, v79
	v_rcp_f32_e32 v76, v76
	v_rcp_f32_e32 v77, v77
	v_add_f32_e32 v78, 1.0, v78
	v_add_f32_e32 v79, 1.0, v79
	v_rcp_f32_e32 v78, v78
	v_rcp_f32_e32 v79, v79
	v_pk_mul_f32 v[72:73], v[72:73], v[76:77]
	v_pk_mul_f32 v[64:65], v[64:65], v[162:163] op_sel_hi:[1,0]
	v_pk_mul_f32 v[66:67], v[66:67], v[162:163] op_sel_hi:[1,0]
	v_pk_mul_f32 v[72:73], v[64:65], v[72:73]
	v_pk_mul_f32 v[64:65], v[74:75], v[78:79]
	v_pk_mul_f32 v[60:61], v[60:61], v[158:159] op_sel_hi:[1,0]
	v_pk_mul_f32 v[74:75], v[66:67], v[64:65]
	v_cvt_pk_bf16_f32 v64, v68, v69
	v_mad_i64_i32 v[68:69], s[8:9], v150, s62, v[112:113]
	v_cvt_pk_bf16_f32 v65, v70, v71
	v_cvt_pk_bf16_f32 v66, v72, v73
	v_cvt_pk_bf16_f32 v67, v74, v75
	v_lshl_add_u64 v[68:69], v[68:69], 0, v[114:115]
	v_mul_f32_e32 v70, 0xbfb8aa3b, v60
	v_mul_f32_e32 v71, 0xbfb8aa3b, v61
	v_pk_mul_f32 v[62:63], v[62:63], v[158:159] op_sel_hi:[1,0]
	v_exp_f32_e32 v70, v70
	v_exp_f32_e32 v71, v71
	global_store_dwordx4 v[68:69], v[64:67], off
	v_pk_mul_f32 v[52:53], v[52:53], v[158:159] op_sel_hi:[1,0]
	v_pk_mul_f32 v[56:57], v[56:57], v[158:159] op_sel_hi:[1,0]
	v_mul_f32_e32 v66, 0xbfb8aa3b, v62
	v_mul_f32_e32 v67, 0xbfb8aa3b, v63
	v_exp_f32_e32 v66, v66
	v_exp_f32_e32 v67, v67
	v_add_f32_e32 v64, 1.0, v70
; #define PG8_GAS __attribute__((address_space(1)))
; __device__ __forceinline__ unsigned pk2_(float lo, float hi) { f32x2c_t v = {lo, hi}; bf16x2c_t b = __builtin_convertvector(v, bf16x2c_t); return __builtin_bit_cast(unsigned, b); }
; __device__ __forceinline__ float silu_f(float x) { return x * __builtin_amdgcn_rcpf(1.0f + __builtin_amdgcn_exp2f(-1.4426950408889634f * x)); }
;     __device__ __forceinline__ void operator()(const f32x4 (&acc)[2][2][4][2], const Unit& u, int wr, int wc, int fr, int fq) const {
;     ...
;             for (int m = 0; m < 4; ++m) {
;                 const int r = row0 + ai * HALF + m * 16; const float s = rs8[ai][m];
;                 float o[8];
; #pragma unroll
;                 for (int n = 0; n < 2; ++n)
; #pragma unroll
;                     for (int i = 0; i < 4; ++i) o[4 * n + i] = silu_f(acc[ai][0][m][n][i] * s) * (acc[ai][1][m][n][i] * s);
;                 u32x4 w; w.x = pk2_(o[0], o[1]); w.y = pk2_(o[2], o[3]); w.z = pk2_(o[4], o[5]); w.w = pk2_(o[6], o[7]);
;                 *(PG8_GAS u32x4*)(O + (size_t)r * 2816 + col0) = w;
;             }
	v_add_f32_e32 v65, 1.0, v71
	v_rcp_f32_e32 v64, v64
	v_rcp_f32_e32 v65, v65
	v_add_f32_e32 v66, 1.0, v66
	v_add_f32_e32 v67, 1.0, v67
	v_rcp_f32_e32 v66, v66
	v_rcp_f32_e32 v67, v67
	v_pk_mul_f32 v[60:61], v[60:61], v[64:65]
	v_pk_mul_f32 v[54:55], v[54:55], v[158:159] op_sel_hi:[1,0]
	v_pk_mul_f32 v[52:53], v[52:53], v[60:61]
	v_pk_mul_f32 v[60:61], v[62:63], v[66:67]
	v_mul_f32_e32 v62, 0xbfb8aa3b, v56
	v_mul_f32_e32 v63, 0xbfb8aa3b, v57
	v_exp_f32_e32 v62, v62
	v_exp_f32_e32 v63, v63
	v_pk_mul_f32 v[58:59], v[58:59], v[158:159] op_sel_hi:[1,0]
	v_pk_mul_f32 v[54:55], v[54:55], v[60:61]
	v_add_f32_e32 v60, 1.0, v62
	v_add_f32_e32 v61, 1.0, v63
	v_mul_f32_e32 v62, 0xbfb8aa3b, v58
	v_mul_f32_e32 v63, 0xbfb8aa3b, v59
	v_exp_f32_e32 v62, v62
	v_exp_f32_e32 v63, v63
	v_rcp_f32_e32 v60, v60
	v_rcp_f32_e32 v61, v61
	v_add_f32_e32 v62, 1.0, v62
	v_add_f32_e32 v63, 1.0, v63
	v_rcp_f32_e32 v62, v62
	v_rcp_f32_e32 v63, v63
	v_pk_mul_f32 v[56:57], v[56:57], v[60:61]
	v_pk_mul_f32 v[48:49], v[48:49], v[158:159] op_sel_hi:[1,0]
	v_pk_mul_f32 v[50:51], v[50:51], v[158:159] op_sel_hi:[1,0]
	v_pk_mul_f32 v[56:57], v[48:49], v[56:57]
	v_pk_mul_f32 v[48:49], v[58:59], v[62:63]
	v_pk_mul_f32 v[44:45], v[44:45], v[154:155] op_sel_hi:[1,0]
	v_pk_mul_f32 v[58:59], v[50:51], v[48:49]
	v_cvt_pk_bf16_f32 v48, v52, v53
	v_mad_i64_i32 v[52:53], s[8:9], v146, s62, v[112:113]
	v_cvt_pk_bf16_f32 v49, v54, v55
	v_cvt_pk_bf16_f32 v50, v56, v57
	v_cvt_pk_bf16_f32 v51, v58, v59
	v_lshl_add_u64 v[52:53], v[52:53], 0, v[114:115]
	v_mul_f32_e32 v54, 0xbfb8aa3b, v44
	v_mul_f32_e32 v55, 0xbfb8aa3b, v45
	v_pk_mul_f32 v[46:47], v[46:47], v[154:155] op_sel_hi:[1,0]
	v_exp_f32_e32 v54, v54
	v_exp_f32_e32 v55, v55
	global_store_dwordx4 v[52:53], v[48:51], off
	v_pk_mul_f32 v[36:37], v[36:37], v[154:155] op_sel_hi:[1,0]
	v_pk_mul_f32 v[40:41], v[40:41], v[154:155] op_sel_hi:[1,0]
	v_mul_f32_e32 v50, 0xbfb8aa3b, v46
	v_mul_f32_e32 v51, 0xbfb8aa3b, v47
	v_exp_f32_e32 v50, v50
	v_exp_f32_e32 v51, v51
	v_add_f32_e32 v48, 1.0, v54
	v_add_f32_e32 v49, 1.0, v55
	v_rcp_f32_e32 v48, v48
	v_rcp_f32_e32 v49, v49
	v_add_f32_e32 v50, 1.0, v50
	v_add_f32_e32 v51, 1.0, v51
	v_rcp_f32_e32 v50, v50
	v_rcp_f32_e32 v51, v51
	v_pk_mul_f32 v[44:45], v[44:45], v[48:49]
	v_pk_mul_f32 v[38:39], v[38:39], v[154:155] op_sel_hi:[1,0]
	v_pk_mul_f32 v[36:37], v[36:37], v[44:45]
	v_pk_mul_f32 v[44:45], v[46:47], v[50:51]
	v_mul_f32_e32 v46, 0xbfb8aa3b, v40
	v_mul_f32_e32 v47, 0xbfb8aa3b, v41
	v_exp_f32_e32 v46, v46
	v_exp_f32_e32 v47, v47
	v_pk_mul_f32 v[42:43], v[42:43], v[154:155] op_sel_hi:[1,0]
	v_pk_mul_f32 v[38:39], v[38:39], v[44:45]
	v_add_f32_e32 v44, 1.0, v46
	v_add_f32_e32 v45, 1.0, v47
	v_mul_f32_e32 v46, 0xbfb8aa3b, v42
	v_mul_f32_e32 v47, 0xbfb8aa3b, v43
	v_exp_f32_e32 v46, v46
	v_exp_f32_e32 v47, v47
	v_rcp_f32_e32 v44, v44
	v_rcp_f32_e32 v45, v45
	v_add_f32_e32 v46, 1.0, v46
	v_add_f32_e32 v47, 1.0, v47
	v_rcp_f32_e32 v46, v46
	v_rcp_f32_e32 v47, v47
	v_pk_mul_f32 v[40:41], v[40:41], v[44:45]
	v_pk_mul_f32 v[32:33], v[32:33], v[154:155] op_sel_hi:[1,0]
	v_pk_mul_f32 v[34:35], v[34:35], v[154:155] op_sel_hi:[1,0]
	v_pk_mul_f32 v[40:41], v[32:33], v[40:41]
	v_pk_mul_f32 v[32:33], v[42:43], v[46:47]
	v_pk_mul_f32 v[28:29], v[28:29], v[148:149] op_sel_hi:[1,0]
	v_pk_mul_f32 v[42:43], v[34:35], v[32:33]
	v_cvt_pk_bf16_f32 v32, v36, v37
	v_mad_i64_i32 v[36:37], s[8:9], v144, s62, v[112:113]
	v_cvt_pk_bf16_f32 v33, v38, v39
	v_cvt_pk_bf16_f32 v34, v40, v41
	v_cvt_pk_bf16_f32 v35, v42, v43
	v_lshl_add_u64 v[36:37], v[36:37], 0, v[114:115]
	v_mul_f32_e32 v38, 0xbfb8aa3b, v28
	v_mul_f32_e32 v39, 0xbfb8aa3b, v29
	v_pk_mul_f32 v[30:31], v[30:31], v[148:149] op_sel_hi:[1,0]
	v_exp_f32_e32 v38, v38
	v_exp_f32_e32 v39, v39
	global_store_dwordx4 v[36:37], v[32:35], off
	v_pk_mul_f32 v[20:21], v[20:21], v[148:149] op_sel_hi:[1,0]
; #define PG8_GAS __attribute__((address_space(1)))
; __device__ __forceinline__ unsigned pk2_(float lo, float hi) { f32x2c_t v = {lo, hi}; bf16x2c_t b = __builtin_convertvector(v, bf16x2c_t); return __builtin_bit_cast(unsigned, b); }
; __device__ __forceinline__ float silu_f(float x) { return x * __builtin_amdgcn_rcpf(1.0f + __builtin_amdgcn_exp2f(-1.4426950408889634f * x)); }
;     __device__ __forceinline__ void operator()(const f32x4 (&acc)[2][2][4][2], const Unit& u, int wr, int wc, int fr, int fq) const {
;     ...
;             for (int m = 0; m < 4; ++m) {
;                 const int r = row0 + ai * HALF + m * 16; const float s = rs8[ai][m];
;                 float o[8];
; #pragma unroll
;                 for (int n = 0; n < 2; ++n)
; #pragma unroll
;                     for (int i = 0; i < 4; ++i) o[4 * n + i] = silu_f(acc[ai][0][m][n][i] * s) * (acc[ai][1][m][n][i] * s);
;                 u32x4 w; w.x = pk2_(o[0], o[1]); w.y = pk2_(o[2], o[3]); w.z = pk2_(o[4], o[5]); w.w = pk2_(o[6], o[7]);
;                 *(PG8_GAS u32x4*)(O + (size_t)r * 2816 + col0) = w;
;             }
	v_pk_mul_f32 v[24:25], v[24:25], v[148:149] op_sel_hi:[1,0]
	v_mul_f32_e32 v34, 0xbfb8aa3b, v30
	v_mul_f32_e32 v35, 0xbfb8aa3b, v31
	v_exp_f32_e32 v34, v34
	v_exp_f32_e32 v35, v35
	v_add_f32_e32 v32, 1.0, v38
	v_add_f32_e32 v33, 1.0, v39
	v_rcp_f32_e32 v32, v32
	v_rcp_f32_e32 v33, v33
	v_add_f32_e32 v34, 1.0, v34
	v_add_f32_e32 v35, 1.0, v35
	v_rcp_f32_e32 v34, v34
	v_rcp_f32_e32 v35, v35
	v_pk_mul_f32 v[28:29], v[28:29], v[32:33]
	v_pk_mul_f32 v[22:23], v[22:23], v[148:149] op_sel_hi:[1,0]
	v_pk_mul_f32 v[20:21], v[20:21], v[28:29]
	v_pk_mul_f32 v[28:29], v[30:31], v[34:35]
	v_mul_f32_e32 v30, 0xbfb8aa3b, v24
	v_mul_f32_e32 v31, 0xbfb8aa3b, v25
	v_exp_f32_e32 v30, v30
	v_exp_f32_e32 v31, v31
	v_pk_mul_f32 v[26:27], v[26:27], v[148:149] op_sel_hi:[1,0]
	v_pk_mul_f32 v[22:23], v[22:23], v[28:29]
	v_add_f32_e32 v28, 1.0, v30
	v_add_f32_e32 v29, 1.0, v31
	v_mul_f32_e32 v30, 0xbfb8aa3b, v26
	v_mul_f32_e32 v31, 0xbfb8aa3b, v27
	v_exp_f32_e32 v30, v30
	v_exp_f32_e32 v31, v31
	v_rcp_f32_e32 v28, v28
	v_rcp_f32_e32 v29, v29
	v_add_f32_e32 v30, 1.0, v30
	v_add_f32_e32 v31, 1.0, v31
	v_rcp_f32_e32 v30, v30
	v_rcp_f32_e32 v31, v31
	v_pk_mul_f32 v[24:25], v[24:25], v[28:29]
	v_pk_mul_f32 v[16:17], v[16:17], v[148:149] op_sel_hi:[1,0]
	v_pk_mul_f32 v[18:19], v[18:19], v[148:149] op_sel_hi:[1,0]
	v_pk_mul_f32 v[24:25], v[16:17], v[24:25]
	v_pk_mul_f32 v[16:17], v[26:27], v[30:31]
	v_pk_mul_f32 v[12:13], v[12:13], v[132:133] op_sel_hi:[1,0]
	v_pk_mul_f32 v[26:27], v[18:19], v[16:17]
	v_cvt_pk_bf16_f32 v16, v20, v21
	v_mad_i64_i32 v[20:21], s[8:9], v142, s62, v[112:113]
	v_cvt_pk_bf16_f32 v17, v22, v23
	v_cvt_pk_bf16_f32 v18, v24, v25
	v_cvt_pk_bf16_f32 v19, v26, v27
	v_lshl_add_u64 v[20:21], v[20:21], 0, v[114:115]
	v_mul_f32_e32 v22, 0xbfb8aa3b, v12
	v_mul_f32_e32 v23, 0xbfb8aa3b, v13
	v_pk_mul_f32 v[14:15], v[14:15], v[132:133] op_sel_hi:[1,0]
	v_exp_f32_e32 v22, v22
	v_exp_f32_e32 v23, v23
	global_store_dwordx4 v[20:21], v[16:19], off
	v_pk_mul_f32 v[4:5], v[4:5], v[132:133] op_sel_hi:[1,0]
	v_pk_mul_f32 v[8:9], v[8:9], v[132:133] op_sel_hi:[1,0]
	v_mul_f32_e32 v18, 0xbfb8aa3b, v14
	v_mul_f32_e32 v19, 0xbfb8aa3b, v15
	v_exp_f32_e32 v18, v18
	v_exp_f32_e32 v19, v19
	v_add_f32_e32 v16, 1.0, v22
	v_add_f32_e32 v17, 1.0, v23
	v_rcp_f32_e32 v16, v16
	v_rcp_f32_e32 v17, v17
	v_add_f32_e32 v18, 1.0, v18
	v_add_f32_e32 v19, 1.0, v19
	v_rcp_f32_e32 v18, v18
	v_rcp_f32_e32 v19, v19
	v_pk_mul_f32 v[12:13], v[12:13], v[16:17]
	v_pk_mul_f32 v[6:7], v[6:7], v[132:133] op_sel_hi:[1,0]
	v_pk_mul_f32 v[4:5], v[4:5], v[12:13]
	v_pk_mul_f32 v[12:13], v[14:15], v[18:19]
	v_mul_f32_e32 v14, 0xbfb8aa3b, v8
	v_mul_f32_e32 v15, 0xbfb8aa3b, v9
	v_exp_f32_e32 v14, v14
	v_exp_f32_e32 v15, v15
	v_pk_mul_f32 v[10:11], v[10:11], v[132:133] op_sel_hi:[1,0]
	v_pk_mul_f32 v[6:7], v[6:7], v[12:13]
	v_add_f32_e32 v12, 1.0, v14
	v_add_f32_e32 v13, 1.0, v15
	v_mul_f32_e32 v14, 0xbfb8aa3b, v10
	v_mul_f32_e32 v15, 0xbfb8aa3b, v11
	v_exp_f32_e32 v14, v14
	v_exp_f32_e32 v15, v15
	v_rcp_f32_e32 v12, v12
	v_rcp_f32_e32 v13, v13
	v_add_f32_e32 v14, 1.0, v14
	v_add_f32_e32 v15, 1.0, v15
	v_rcp_f32_e32 v14, v14
	v_rcp_f32_e32 v15, v15
	v_pk_mul_f32 v[8:9], v[8:9], v[12:13]
	v_pk_mul_f32 v[0:1], v[0:1], v[132:133] op_sel_hi:[1,0]
	v_pk_mul_f32 v[2:3], v[2:3], v[132:133] op_sel_hi:[1,0]
	v_pk_mul_f32 v[8:9], v[0:1], v[8:9]
	v_pk_mul_f32 v[0:1], v[10:11], v[14:15]
	s_andn2_b64 vcc, exec, s[6:7]
	v_pk_mul_f32 v[10:11], v[2:3], v[0:1]
	v_cvt_pk_bf16_f32 v0, v4, v5
	v_mad_i64_i32 v[4:5], s[8:9], v140, s62, v[112:113]
	v_cvt_pk_bf16_f32 v1, v6, v7
	v_cvt_pk_bf16_f32 v2, v8, v9
	v_cvt_pk_bf16_f32 v3, v10, v11
	v_lshl_add_u64 v[4:5], v[4:5], 0, v[114:115]
	s_mov_b64 s[6:7], -1
	global_store_dwordx4 v[4:5], v[0:3], off
	s_cbranch_vccnz .LBB0_1654
	s_andn2_b64 vcc, exec, s[12:13]
	s_cbranch_vccnz .LBB0_1653
	s_barrier
	s_branch .LBB0_1653
